# MFMA blocks: mid-block s_setprio 0/1 flip removed (32 MFMAs issue as one uninterrupted reuse chain)
# baseline (speedup 1.0000x reference)
; #define PG8_LAS __attribute__((address_space(3)))
; #define PG8_STAGE(bufoff, gbase, voff) do { _Pragma("unroll") for (int _i = 0; _i < 2; ++_i) \
;         __builtin_amdgcn_global_load_lds((const unsigned*)((const char*)(gbase) + (voff)[_i]), (PG8_LAS unsigned*)(lds + (bufoff) + ldsw + _i * 8192), 16, 0, 0); } while (0)
; #define PG8_LDA(dst, b, h) do { _Pragma("unroll") for (int m = 0; m < 4; ++m) _Pragma("unroll") for (int k = 0; k < 2; ++k) dst[m][k] = *(const PG8_LAS bf16x8*)(lds + PG8_SA(b, h) + aoff + m * 2048 + k * 1024); } while (0)
; template <class Epi, class Sched, bool ALIGN_EPI = false, bool SP2 = false, bool RS = false, bool BPRE = false>
; __device__ __forceinline__ void gemm_phase(PG8_LAS unsigned char* lds, const Gemm g, const Sched& S, const Epi& E, const float* rs_ss = nullptr, PG8_LAS float* rs_tab = nullptr) {
;     ...
;         const bool has_next = S.next(ui + 1, nxt);
;         const char* nA = has_next ? (const char*)g.A + (size_t)nxt.pm * tstep : cA; const char* nB = has_next ? (const char*)g.Bt + (size_t)nxt.pn * tstep : cB;
;         for (int t = 0; t < nt; t += 2) {
;             const bool last = (t == nt - 2);
;             if constexpr (RS) { if (t == 16 || t == 32) { const PG8_LAS float* tp = rs_tab + (ui & 1) * 768 + (t == 32 ? 256 : 0);
;                 _Pragma("unroll") for (int a = 0; a < 2; ++a) _Pragma("unroll") for (int m = 0; m < 4; ++m) { const float f = tp[a * HALF + wr * 64 + m * 16 + fr];
;                     _Pragma("unroll") for (int b = 0; b < 2; ++b) _Pragma("unroll") for (int n = 0; n < 2; ++n) acc[a][b][m][n] = acc[a][b][m][n] * f; } } }
;             const char* a1 = cA + (size_t)(t + 1) * kstep;
;             const char* a2 = last ? nA : cA + (size_t)(t + 2) * kstep; const char* b2 = last ? nB : cB + (size_t)(t + 2) * kstep;
;             const char* a3 = a2 + kstep; const char* b3 = b2 + kstep;
;             if (last && has_next) S.a_ready(nxt);
;             if constexpr (SP2) {
;             PG8_LDB(B0, 0, 0); PG8_LDB(B1, 0, 1); PG8_SCHED; PG8_LDA(At, 0, 0); PG8_STAGE(PG8_SA(1, 1), a1 + hstep, voffA);
;             PG8_WAIT_V(8); PG8_WAIT_L(0); PG8_BAR; PG8_MMA(0, 0, At, B0); PG8_MMA(0, 1, At, B1); PG8_BAR; PG8_SCHED;
;             PG8_LDA(At, 0, 1); PG8_STAGE(PG8_SB(0, 0), b2, voffB); PG8_STAGE(PG8_SB(0, 1), b2 + hstep, voffB); PG8_STAGE(PG8_SA(0, 0), a2, voffA);
.LBB0_195:
	s_ashr_i32 s19, s18, 31
	s_lshl_b64 s[20:21], s[18:19], 20
	s_add_u32 s20, s30, s20
	s_addc_u32 s21, s31, s21
	s_and_b64 s[44:45], s[6:7], exec
	s_cselect_b32 s5, s21, s57
	s_cselect_b32 s19, s20, s56
	s_ashr_i32 s17, s16, 31
	s_lshl_b64 s[44:45], s[16:17], 20
	s_add_u32 s44, s24, s44
	s_addc_u32 s45, s25, s45
	s_and_b64 s[60:61], s[6:7], exec
	s_cselect_b32 s17, s45, s59
	s_cselect_b32 s47, s44, s58
	s_add_u32 s56, s56, 0x84000
	s_addc_u32 s57, s57, 0
	s_add_u32 s87, s58, 0x8000
	s_addc_u32 s88, s59, 0
	s_mov_b32 s89, -2
	s_waitcnt lgkmcnt(0)
	ds_read_b128 v[130:133], v161
	ds_read_b128 v[134:137], v161 offset:1024
	ds_read_b128 v[152:155], v161 offset:2048
	ds_read_b128 v[156:159], v161 offset:3072
	ds_read_b128 v[166:169], v162
	ds_read_b128 v[170:173], v162 offset:1024
	ds_read_b128 v[174:177], v162 offset:2048
	ds_read_b128 v[182:185], v162 offset:3072
	s_add_u32 s58, s56, 0xfff84000
	s_addc_u32 s59, s57, -1
	s_cmp_eq_u32 s89, 28
	s_cselect_b32 s70, s19, s58
	s_cselect_b32 s71, s5, s59
	s_cselect_b32 s60, s47, s87
	s_cselect_b32 s61, s17, s88
	s_add_u32 s58, s70, 0x4000
	s_addc_u32 s59, s71, 0
	v_lshl_add_u64 v[178:179], s[56:57], 0, v[138:139]
	s_add_i32 m0, s72, 0xc000
	ds_read_b128 v[186:189], v163
	ds_read_b128 v[190:193], v163 offset:1024
	ds_read_b128 v[194:197], v163 offset:2048
	ds_read_b128 v[198:201], v163 offset:3072
	ds_read_b128 v[202:205], v163 offset:4096
	ds_read_b128 v[206:209], v163 offset:5120
	ds_read_b128 v[210:213], v163 offset:6144
	ds_read_b128 v[214:217], v163 offset:7168
	global_load_lds_dwordx4 v[178:179], off
	v_lshl_add_u64 v[178:179], s[56:57], 0, v[146:147]
	s_add_i32 m0, s72, 0xe000
	s_nop 0
	global_load_lds_dwordx4 v[178:179], off
	s_waitcnt vmcnt(8)
	s_waitcnt lgkmcnt(0)
	s_barrier
	s_setprio 1
	s_waitcnt lgkmcnt(0)
	v_mfma_f32_16x16x32_bf16 v[126:129], v[130:133], v[186:189], 0
	v_mfma_f32_16x16x32_bf16 v[126:129], v[134:137], v[190:193], v[126:129]
	v_mfma_f32_16x16x32_bf16 v[122:125], v[156:159], v[190:193], 0
	v_mfma_f32_16x16x32_bf16 v[122:125], v[152:155], v[186:189], v[122:125]
	v_mfma_f32_16x16x32_bf16 v[106:109], v[152:155], v[194:197], 0
	v_mfma_f32_16x16x32_bf16 v[106:109], v[156:159], v[198:201], v[106:109]
	v_mfma_f32_16x16x32_bf16 v[110:113], v[134:137], v[198:201], 0
	v_mfma_f32_16x16x32_bf16 v[110:113], v[130:133], v[194:197], v[110:113]
	v_mfma_f32_16x16x32_bf16 v[94:97], v[130:133], v[202:205], 0
	v_mfma_f32_16x16x32_bf16 v[94:97], v[134:137], v[206:209], v[94:97]
	v_mfma_f32_16x16x32_bf16 v[90:93], v[156:159], v[206:209], 0
	v_mfma_f32_16x16x32_bf16 v[90:93], v[152:155], v[202:205], v[90:93]
	v_mfma_f32_16x16x32_bf16 v[74:77], v[152:155], v[210:213], 0
	v_mfma_f32_16x16x32_bf16 v[74:77], v[156:159], v[214:217], v[74:77]
	v_mfma_f32_16x16x32_bf16 v[78:81], v[134:137], v[214:217], 0
	v_mfma_f32_16x16x32_bf16 v[78:81], v[130:133], v[210:213], v[78:81]
	v_mfma_f32_16x16x32_bf16 v[70:73], v[166:169], v[210:213], 0
	v_mfma_f32_16x16x32_bf16 v[70:73], v[170:173], v[214:217], v[70:73]
	v_mfma_f32_16x16x32_bf16 v[66:69], v[182:185], v[214:217], 0
	v_mfma_f32_16x16x32_bf16 v[66:69], v[174:177], v[210:213], v[66:69]
	v_mfma_f32_16x16x32_bf16 v[82:85], v[174:177], v[202:205], 0
	v_mfma_f32_16x16x32_bf16 v[82:85], v[182:185], v[206:209], v[82:85]
	v_mfma_f32_16x16x32_bf16 v[86:89], v[170:173], v[206:209], 0
	v_mfma_f32_16x16x32_bf16 v[86:89], v[166:169], v[202:205], v[86:89]
	v_mfma_f32_16x16x32_bf16 v[102:105], v[166:169], v[194:197], 0
	v_mfma_f32_16x16x32_bf16 v[102:105], v[170:173], v[198:201], v[102:105]
	v_mfma_f32_16x16x32_bf16 v[98:101], v[182:185], v[198:201], 0
	v_mfma_f32_16x16x32_bf16 v[98:101], v[174:177], v[194:197], v[98:101]
	v_mfma_f32_16x16x32_bf16 v[114:117], v[174:177], v[186:189], 0
	v_mfma_f32_16x16x32_bf16 v[114:117], v[182:185], v[190:193], v[114:117]
	v_mfma_f32_16x16x32_bf16 v[118:121], v[170:173], v[190:193], 0
	v_mfma_f32_16x16x32_bf16 v[118:121], v[166:169], v[186:189], v[118:121]
	s_setprio 0
	s_barrier
	s_add_i32 s90, s83, s15
	v_lshl_add_u64 v[178:179], s[60:61], 0, v[138:139]
	s_mov_b32 m0, s90
	ds_read_b128 v[186:189], v163 offset:16384
	ds_read_b128 v[190:193], v163 offset:17408
	ds_read_b128 v[194:197], v163 offset:18432
	ds_read_b128 v[198:201], v163 offset:19456
	ds_read_b128 v[202:205], v163 offset:20480
	ds_read_b128 v[206:209], v163 offset:21504
	ds_read_b128 v[210:213], v163 offset:22528
	ds_read_b128 v[214:217], v163 offset:23552
	global_load_lds_dwordx4 v[178:179], off
	s_add_i32 m0, s90, 0x2000
	s_add_u32 s90, s60, 0x80000
	v_lshl_add_u64 v[178:179], s[60:61], 0, v[140:141]
	s_addc_u32 s91, s61, 0
	s_add_i32 s92, s86, s15
	global_load_lds_dwordx4 v[178:179], off
	v_lshl_add_u64 v[178:179], s[90:91], 0, v[138:139]
	s_mov_b32 m0, s92
	s_nop 0
	global_load_lds_dwordx4 v[178:179], off
	v_lshl_add_u64 v[178:179], s[90:91], 0, v[140:141]
	s_add_i32 m0, s92, 0x2000
	s_nop 0
	global_load_lds_dwordx4 v[178:179], off
	v_lshl_add_u64 v[178:179], s[70:71], 0, v[138:139]
	s_mov_b32 m0, s72
	s_nop 0
	global_load_lds_dwordx4 v[178:179], off
	v_lshl_add_u64 v[178:179], s[70:71], 0, v[140:141]
	s_mov_b32 m0, s73
	s_nop 0
	global_load_lds_dwordx4 v[178:179], off
	s_waitcnt vmcnt(8)
	s_waitcnt lgkmcnt(0)
	s_barrier
; #define PG8_STAGE(bufoff, gbase, voff) do { _Pragma("unroll") for (int _i = 0; _i < 2; ++_i) \
;         __builtin_amdgcn_global_load_lds((const unsigned*)((const char*)(gbase) + (voff)[_i]), (PG8_LAS unsigned*)(lds + (bufoff) + ldsw + _i * 8192), 16, 0, 0); } while (0)
; #define PG8_LDA(dst, b, h) do { _Pragma("unroll") for (int m = 0; m < 4; ++m) _Pragma("unroll") for (int k = 0; k < 2; ++k) dst[m][k] = *(const PG8_LAS bf16x8*)(lds + PG8_SA(b, h) + aoff + m * 2048 + k * 1024); } while (0)
; #define PG8_LDB(dst, b, h) do { _Pragma("unroll") for (int n = 0; n < 2; ++n) _Pragma("unroll") for (int k = 0; k < 2; ++k) dst[n][k] = *(const PG8_LAS bf16x8*)(lds + PG8_SB(b, h) + boff + n * 2048 + k * 1024); } while (0)
; #define PG8_MMA(ai, bj, At, Bt) do { __builtin_amdgcn_s_setprio(1); _Pragma("unroll") for (int m = 0; m < 4; ++m) _Pragma("unroll") for (int n = 0; n < 2; ++n) _Pragma("unroll") for (int k = 0; k < 2; ++k) \
;         acc[ai][bj][m][n] = __builtin_amdgcn_mfma_f32_16x16x32_bf16(Bt[n][k], At[m][k], acc[ai][bj][m][n], 0, 0, 0); __builtin_amdgcn_s_setprio(0); } while (0)
; #define PG8_WAIT_V(n) asm volatile("s_waitcnt vmcnt(" #n ")" ::: "memory")
; #define PG8_WAIT_L(n) asm volatile("s_waitcnt lgkmcnt(" #n ")" ::: "memory")
; #define PG8_BAR __builtin_amdgcn_s_barrier()
; #define PG8_SCHED __builtin_amdgcn_sched_barrier(0)
; template <class Epi, class Sched, bool ALIGN_EPI = false, bool SP2 = false, bool RS = false, bool BPRE = false>
; __device__ __forceinline__ void gemm_phase(PG8_LAS unsigned char* lds, const Gemm g, const Sched& S, const Epi& E, const float* rs_ss = nullptr, PG8_LAS float* rs_tab = nullptr) {
;     ...
;             PG8_WAIT_V(8); PG8_WAIT_L(0); PG8_BAR; PG8_MMA(1, 0, At, B0); PG8_MMA(1, 1, At, B1); PG8_BAR; PG8_SCHED;
;             PG8_LDB(B0, 1, 0); PG8_LDB(B1, 1, 1); PG8_SCHED; PG8_LDA(At, 1, 0); PG8_STAGE(PG8_SA(0, 1), a2 + hstep, voffA);
;             PG8_WAIT_V(8); PG8_WAIT_L(0); PG8_BAR; PG8_MMA(0, 0, At, B0); PG8_MMA(0, 1, At, B1); PG8_BAR; PG8_SCHED;
	s_setprio 1
	s_waitcnt lgkmcnt(0)
	v_mfma_f32_16x16x32_bf16 v[62:65], v[130:133], v[186:189], 0
	v_mfma_f32_16x16x32_bf16 v[62:65], v[134:137], v[190:193], v[62:65]
	v_mfma_f32_16x16x32_bf16 v[58:61], v[156:159], v[190:193], 0
	v_mfma_f32_16x16x32_bf16 v[58:61], v[152:155], v[186:189], v[58:61]
	v_mfma_f32_16x16x32_bf16 v[42:45], v[152:155], v[194:197], 0
	v_mfma_f32_16x16x32_bf16 v[42:45], v[156:159], v[198:201], v[42:45]
	v_mfma_f32_16x16x32_bf16 v[46:49], v[134:137], v[198:201], 0
	v_mfma_f32_16x16x32_bf16 v[46:49], v[130:133], v[194:197], v[46:49]
	v_mfma_f32_16x16x32_bf16 v[30:33], v[130:133], v[202:205], 0
	v_mfma_f32_16x16x32_bf16 v[30:33], v[134:137], v[206:209], v[30:33]
	v_mfma_f32_16x16x32_bf16 v[26:29], v[156:159], v[206:209], 0
	v_mfma_f32_16x16x32_bf16 v[26:29], v[152:155], v[202:205], v[26:29]
	v_mfma_f32_16x16x32_bf16 v[10:13], v[152:155], v[210:213], 0
	v_mfma_f32_16x16x32_bf16 v[10:13], v[156:159], v[214:217], v[10:13]
	v_mfma_f32_16x16x32_bf16 v[14:17], v[134:137], v[214:217], 0
	v_mfma_f32_16x16x32_bf16 v[14:17], v[130:133], v[210:213], v[14:17]
	v_mfma_f32_16x16x32_bf16 v[6:9], v[166:169], v[210:213], 0
	v_mfma_f32_16x16x32_bf16 v[6:9], v[170:173], v[214:217], v[6:9]
	v_mfma_f32_16x16x32_bf16 v[2:5], v[182:185], v[214:217], 0
	v_mfma_f32_16x16x32_bf16 v[2:5], v[174:177], v[210:213], v[2:5]
	v_mfma_f32_16x16x32_bf16 v[18:21], v[174:177], v[202:205], 0
	v_mfma_f32_16x16x32_bf16 v[18:21], v[182:185], v[206:209], v[18:21]
	v_mfma_f32_16x16x32_bf16 v[22:25], v[170:173], v[206:209], 0
	v_mfma_f32_16x16x32_bf16 v[22:25], v[166:169], v[202:205], v[22:25]
	v_mfma_f32_16x16x32_bf16 v[38:41], v[166:169], v[194:197], 0
	v_mfma_f32_16x16x32_bf16 v[38:41], v[170:173], v[198:201], v[38:41]
	v_mfma_f32_16x16x32_bf16 v[34:37], v[182:185], v[198:201], 0
	v_mfma_f32_16x16x32_bf16 v[34:37], v[174:177], v[194:197], v[34:37]
	v_mfma_f32_16x16x32_bf16 v[50:53], v[174:177], v[186:189], 0
	v_mfma_f32_16x16x32_bf16 v[50:53], v[182:185], v[190:193], v[50:53]
	v_mfma_f32_16x16x32_bf16 v[54:57], v[170:173], v[190:193], 0
	v_mfma_f32_16x16x32_bf16 v[54:57], v[166:169], v[186:189], v[54:57]
	s_setprio 0
	s_barrier
	s_add_i32 s90, 0, 0x18000
	v_add_u32_e32 v143, s90, v160
	s_add_i32 s91, 0, 0x1c000
	ds_read_b128 v[130:133], v143
	ds_read_b128 v[134:137], v143 offset:1024
	ds_read_b128 v[152:155], v143 offset:2048
	ds_read_b128 v[156:159], v143 offset:3072
	v_add_u32_e32 v143, s91, v160
	ds_read_b128 v[166:169], v143
	ds_read_b128 v[170:173], v143 offset:1024
	ds_read_b128 v[174:177], v143 offset:2048
	ds_read_b128 v[182:185], v143 offset:3072
	s_add_u32 s70, s70, 0x80000
	s_addc_u32 s71, s71, 0
	s_mov_b32 m0, s74
	v_lshl_add_u64 v[178:179], s[70:71], 0, v[138:139]
	ds_read_b128 v[186:189], v163 offset:32768
	ds_read_b128 v[190:193], v163 offset:33792
	ds_read_b128 v[194:197], v163 offset:34816
	ds_read_b128 v[198:201], v163 offset:35840
	ds_read_b128 v[202:205], v163 offset:36864
	ds_read_b128 v[206:209], v163 offset:37888
	ds_read_b128 v[210:213], v163 offset:38912
	ds_read_b128 v[214:217], v163 offset:39936
	global_load_lds_dwordx4 v[178:179], off
	v_lshl_add_u64 v[178:179], s[70:71], 0, v[140:141]
	s_mov_b32 m0, s75
	s_nop 0
	global_load_lds_dwordx4 v[178:179], off
	s_waitcnt vmcnt(8)
	s_waitcnt lgkmcnt(0)
	s_barrier
	s_setprio 1
	s_waitcnt lgkmcnt(0)
	v_mfma_f32_16x16x32_bf16 v[126:129], v[130:133], v[186:189], v[126:129]
	v_mfma_f32_16x16x32_bf16 v[126:129], v[134:137], v[190:193], v[126:129]
	v_mfma_f32_16x16x32_bf16 v[122:125], v[156:159], v[190:193], v[122:125]
	v_mfma_f32_16x16x32_bf16 v[122:125], v[152:155], v[186:189], v[122:125]
	v_mfma_f32_16x16x32_bf16 v[106:109], v[152:155], v[194:197], v[106:109]
	v_mfma_f32_16x16x32_bf16 v[106:109], v[156:159], v[198:201], v[106:109]
	v_mfma_f32_16x16x32_bf16 v[110:113], v[134:137], v[198:201], v[110:113]
	v_mfma_f32_16x16x32_bf16 v[110:113], v[130:133], v[194:197], v[110:113]
	v_mfma_f32_16x16x32_bf16 v[94:97], v[130:133], v[202:205], v[94:97]
	v_mfma_f32_16x16x32_bf16 v[94:97], v[134:137], v[206:209], v[94:97]
	v_mfma_f32_16x16x32_bf16 v[90:93], v[156:159], v[206:209], v[90:93]
	v_mfma_f32_16x16x32_bf16 v[90:93], v[152:155], v[202:205], v[90:93]
	v_mfma_f32_16x16x32_bf16 v[74:77], v[152:155], v[210:213], v[74:77]
	v_mfma_f32_16x16x32_bf16 v[74:77], v[156:159], v[214:217], v[74:77]
	v_mfma_f32_16x16x32_bf16 v[78:81], v[134:137], v[214:217], v[78:81]
	v_mfma_f32_16x16x32_bf16 v[78:81], v[130:133], v[210:213], v[78:81]
	v_mfma_f32_16x16x32_bf16 v[70:73], v[166:169], v[210:213], v[70:73]
	v_mfma_f32_16x16x32_bf16 v[70:73], v[170:173], v[214:217], v[70:73]
	v_mfma_f32_16x16x32_bf16 v[66:69], v[182:185], v[214:217], v[66:69]
	v_mfma_f32_16x16x32_bf16 v[66:69], v[174:177], v[210:213], v[66:69]
	v_mfma_f32_16x16x32_bf16 v[82:85], v[174:177], v[202:205], v[82:85]
	v_mfma_f32_16x16x32_bf16 v[82:85], v[182:185], v[206:209], v[82:85]
	v_mfma_f32_16x16x32_bf16 v[86:89], v[170:173], v[206:209], v[86:89]
	v_mfma_f32_16x16x32_bf16 v[86:89], v[166:169], v[202:205], v[86:89]
	v_mfma_f32_16x16x32_bf16 v[102:105], v[166:169], v[194:197], v[102:105]
	v_mfma_f32_16x16x32_bf16 v[102:105], v[170:173], v[198:201], v[102:105]
	v_mfma_f32_16x16x32_bf16 v[98:101], v[182:185], v[198:201], v[98:101]
	v_mfma_f32_16x16x32_bf16 v[98:101], v[174:177], v[194:197], v[98:101]
	v_mfma_f32_16x16x32_bf16 v[114:117], v[174:177], v[186:189], v[114:117]
	v_mfma_f32_16x16x32_bf16 v[114:117], v[182:185], v[190:193], v[114:117]
	v_mfma_f32_16x16x32_bf16 v[118:121], v[170:173], v[190:193], v[118:121]
	v_mfma_f32_16x16x32_bf16 v[118:121], v[166:169], v[186:189], v[118:121]
	s_setprio 0
	s_barrier
; #define PG8_STAGE(bufoff, gbase, voff) do { _Pragma("unroll") for (int _i = 0; _i < 2; ++_i) \
;         __builtin_amdgcn_global_load_lds((const unsigned*)((const char*)(gbase) + (voff)[_i]), (PG8_LAS unsigned*)(lds + (bufoff) + ldsw + _i * 8192), 16, 0, 0); } while (0)
; #define PG8_LDA(dst, b, h) do { _Pragma("unroll") for (int m = 0; m < 4; ++m) _Pragma("unroll") for (int k = 0; k < 2; ++k) dst[m][k] = *(const PG8_LAS bf16x8*)(lds + PG8_SA(b, h) + aoff + m * 2048 + k * 1024); } while (0)
; #define PG8_LDB(dst, b, h) do { _Pragma("unroll") for (int n = 0; n < 2; ++n) _Pragma("unroll") for (int k = 0; k < 2; ++k) dst[n][k] = *(const PG8_LAS bf16x8*)(lds + PG8_SB(b, h) + boff + n * 2048 + k * 1024); } while (0)
; #define PG8_MMA(ai, bj, At, Bt) do { __builtin_amdgcn_s_setprio(1); _Pragma("unroll") for (int m = 0; m < 4; ++m) _Pragma("unroll") for (int n = 0; n < 2; ++n) _Pragma("unroll") for (int k = 0; k < 2; ++k) \
;         acc[ai][bj][m][n] = __builtin_amdgcn_mfma_f32_16x16x32_bf16(Bt[n][k], At[m][k], acc[ai][bj][m][n], 0, 0, 0); __builtin_amdgcn_s_setprio(0); } while (0)
; #define PG8_WAIT_V(n) asm volatile("s_waitcnt vmcnt(" #n ")" ::: "memory")
; #define PG8_WAIT_L(n) asm volatile("s_waitcnt lgkmcnt(" #n ")" ::: "memory")
; #define PG8_BAR __builtin_amdgcn_s_barrier()
; #define PG8_SCHED __builtin_amdgcn_sched_barrier(0)
; template <class Epi, class Sched, bool ALIGN_EPI = false, bool SP2 = false, bool RS = false, bool BPRE = false>
; __device__ __forceinline__ void gemm_phase(PG8_LAS unsigned char* lds, const Gemm g, const Sched& S, const Epi& E, const float* rs_ss = nullptr, PG8_LAS float* rs_tab = nullptr) {
;     ...
;             PG8_LDB(B0, 0, 0); PG8_LDB(B1, 0, 1); PG8_SCHED; PG8_LDA(At, 0, 0); PG8_STAGE(PG8_SA(1, 1), a1 + hstep, voffA);
;             PG8_WAIT_V(8); PG8_WAIT_L(0); PG8_BAR; PG8_MMA(0, 0, At, B0); PG8_MMA(0, 1, At, B1); PG8_BAR; PG8_SCHED;
;     ...
;             PG8_LDA(At, 1, 1); PG8_STAGE(PG8_SB(1, 0), b3, voffB); PG8_STAGE(PG8_SB(1, 1), b3 + hstep, voffB); PG8_STAGE(PG8_SA(1, 0), a3, voffA);
;             PG8_WAIT_V(8); PG8_WAIT_L(0); PG8_BAR; PG8_MMA(1, 0, At, B0); PG8_MMA(1, 1, At, B1); PG8_BAR; PG8_SCHED;
	s_add_u32 s70, s60, 0x4000
	s_addc_u32 s71, s61, 0
	s_add_i32 s90, s90, s15
	v_lshl_add_u64 v[178:179], s[70:71], 0, v[138:139]
	s_mov_b32 m0, s90
	ds_read_b128 v[186:189], v163 offset:49152
	ds_read_b128 v[190:193], v163 offset:50176
	ds_read_b128 v[194:197], v163 offset:51200
	ds_read_b128 v[198:201], v163 offset:52224
	ds_read_b128 v[202:205], v163 offset:53248
	ds_read_b128 v[206:209], v163 offset:54272
	ds_read_b128 v[210:213], v163 offset:55296
	ds_read_b128 v[214:217], v163 offset:56320
	global_load_lds_dwordx4 v[178:179], off
	s_add_i32 m0, s90, 0x2000
	s_add_u32 s60, s60, 0x84000
	v_lshl_add_u64 v[178:179], s[70:71], 0, v[140:141]
	s_addc_u32 s61, s61, 0
	s_add_i32 s70, s91, s15
	global_load_lds_dwordx4 v[178:179], off
	v_lshl_add_u64 v[178:179], s[60:61], 0, v[138:139]
	s_mov_b32 m0, s70
	s_nop 0
	global_load_lds_dwordx4 v[178:179], off
	v_lshl_add_u64 v[178:179], s[60:61], 0, v[140:141]
	s_add_i32 m0, s70, 0x2000
	s_nop 0
	global_load_lds_dwordx4 v[178:179], off
	v_lshl_add_u64 v[178:179], s[58:59], 0, v[138:139]
	s_mov_b32 m0, s79
	s_nop 0
	global_load_lds_dwordx4 v[178:179], off
	v_lshl_add_u64 v[178:179], s[58:59], 0, v[140:141]
	s_mov_b32 m0, s80
	s_nop 0
	global_load_lds_dwordx4 v[178:179], off
	s_waitcnt vmcnt(8)
	s_waitcnt lgkmcnt(0)
	s_barrier
	s_setprio 1
	s_waitcnt lgkmcnt(0)
	v_mfma_f32_16x16x32_bf16 v[62:65], v[130:133], v[186:189], v[62:65]
	v_mfma_f32_16x16x32_bf16 v[62:65], v[134:137], v[190:193], v[62:65]
	v_mfma_f32_16x16x32_bf16 v[58:61], v[156:159], v[190:193], v[58:61]
	v_mfma_f32_16x16x32_bf16 v[58:61], v[152:155], v[186:189], v[58:61]
	v_mfma_f32_16x16x32_bf16 v[42:45], v[152:155], v[194:197], v[42:45]
	v_mfma_f32_16x16x32_bf16 v[42:45], v[156:159], v[198:201], v[42:45]
	v_mfma_f32_16x16x32_bf16 v[46:49], v[134:137], v[198:201], v[46:49]
	v_mfma_f32_16x16x32_bf16 v[46:49], v[130:133], v[194:197], v[46:49]
	v_mfma_f32_16x16x32_bf16 v[30:33], v[130:133], v[202:205], v[30:33]
	v_mfma_f32_16x16x32_bf16 v[30:33], v[134:137], v[206:209], v[30:33]
	v_mfma_f32_16x16x32_bf16 v[26:29], v[156:159], v[206:209], v[26:29]
	v_mfma_f32_16x16x32_bf16 v[26:29], v[152:155], v[202:205], v[26:29]
	v_mfma_f32_16x16x32_bf16 v[10:13], v[152:155], v[210:213], v[10:13]
	v_mfma_f32_16x16x32_bf16 v[10:13], v[156:159], v[214:217], v[10:13]
	v_mfma_f32_16x16x32_bf16 v[14:17], v[134:137], v[214:217], v[14:17]
	v_mfma_f32_16x16x32_bf16 v[14:17], v[130:133], v[210:213], v[14:17]
	v_mfma_f32_16x16x32_bf16 v[6:9], v[166:169], v[210:213], v[6:9]
	v_mfma_f32_16x16x32_bf16 v[6:9], v[170:173], v[214:217], v[6:9]
	v_mfma_f32_16x16x32_bf16 v[2:5], v[182:185], v[214:217], v[2:5]
	v_mfma_f32_16x16x32_bf16 v[2:5], v[174:177], v[210:213], v[2:5]
	v_mfma_f32_16x16x32_bf16 v[18:21], v[174:177], v[202:205], v[18:21]
	v_mfma_f32_16x16x32_bf16 v[18:21], v[182:185], v[206:209], v[18:21]
	v_mfma_f32_16x16x32_bf16 v[22:25], v[170:173], v[206:209], v[22:25]
	v_mfma_f32_16x16x32_bf16 v[22:25], v[166:169], v[202:205], v[22:25]
	v_mfma_f32_16x16x32_bf16 v[38:41], v[166:169], v[194:197], v[38:41]
	v_mfma_f32_16x16x32_bf16 v[38:41], v[170:173], v[198:201], v[38:41]
	v_mfma_f32_16x16x32_bf16 v[34:37], v[182:185], v[198:201], v[34:37]
	v_mfma_f32_16x16x32_bf16 v[34:37], v[174:177], v[194:197], v[34:37]
	v_mfma_f32_16x16x32_bf16 v[50:53], v[174:177], v[186:189], v[50:53]
	v_mfma_f32_16x16x32_bf16 v[50:53], v[182:185], v[190:193], v[50:53]
	v_mfma_f32_16x16x32_bf16 v[54:57], v[170:173], v[190:193], v[54:57]
	v_mfma_f32_16x16x32_bf16 v[54:57], v[166:169], v[186:189], v[54:57]
	s_setprio 0
	s_barrier
	s_add_i32 s89, s89, 2
	s_add_u32 s56, s56, 0x8000
	s_addc_u32 s57, s57, 0
	s_add_u32 s87, s87, 0x8000
	s_addc_u32 s88, s88, 0
.LBB0_196:
	ds_read_b128 v[130:133], v161
	ds_read_b128 v[134:137], v161 offset:1024
	ds_read_b128 v[152:155], v161 offset:2048
	ds_read_b128 v[156:159], v161 offset:3072
	ds_read_b128 v[166:169], v162
	ds_read_b128 v[170:173], v162 offset:1024
	ds_read_b128 v[174:177], v162 offset:2048
	ds_read_b128 v[182:185], v162 offset:3072
	s_add_u32 s58, s56, 0xfff84000
	s_addc_u32 s59, s57, -1
	s_cmp_eq_u32 s89, 28
	s_cselect_b32 s70, s19, s58
	s_cselect_b32 s71, s5, s59
	s_cselect_b32 s60, s47, s87
	s_cselect_b32 s61, s17, s88
	s_add_u32 s58, s70, 0x4000
	s_addc_u32 s59, s71, 0
	v_lshl_add_u64 v[178:179], s[56:57], 0, v[138:139]
	s_add_i32 m0, s72, 0xc000
	ds_read_b128 v[186:189], v163
	ds_read_b128 v[190:193], v163 offset:1024
	ds_read_b128 v[194:197], v163 offset:2048
	ds_read_b128 v[198:201], v163 offset:3072
	ds_read_b128 v[202:205], v163 offset:4096
	ds_read_b128 v[206:209], v163 offset:5120
	ds_read_b128 v[210:213], v163 offset:6144
	ds_read_b128 v[214:217], v163 offset:7168
	global_load_lds_dwordx4 v[178:179], off
	v_lshl_add_u64 v[178:179], s[56:57], 0, v[146:147]
	s_add_i32 m0, s72, 0xe000
	s_nop 0
	global_load_lds_dwordx4 v[178:179], off
	s_waitcnt vmcnt(8)
	s_waitcnt lgkmcnt(0)
	s_barrier
; #define PG8_STAGE(bufoff, gbase, voff) do { _Pragma("unroll") for (int _i = 0; _i < 2; ++_i) \
;         __builtin_amdgcn_global_load_lds((const unsigned*)((const char*)(gbase) + (voff)[_i]), (PG8_LAS unsigned*)(lds + (bufoff) + ldsw + _i * 8192), 16, 0, 0); } while (0)
; #define PG8_LDA(dst, b, h) do { _Pragma("unroll") for (int m = 0; m < 4; ++m) _Pragma("unroll") for (int k = 0; k < 2; ++k) dst[m][k] = *(const PG8_LAS bf16x8*)(lds + PG8_SA(b, h) + aoff + m * 2048 + k * 1024); } while (0)
; #define PG8_LDB(dst, b, h) do { _Pragma("unroll") for (int n = 0; n < 2; ++n) _Pragma("unroll") for (int k = 0; k < 2; ++k) dst[n][k] = *(const PG8_LAS bf16x8*)(lds + PG8_SB(b, h) + boff + n * 2048 + k * 1024); } while (0)
; #define PG8_MMA(ai, bj, At, Bt) do { __builtin_amdgcn_s_setprio(1); _Pragma("unroll") for (int m = 0; m < 4; ++m) _Pragma("unroll") for (int n = 0; n < 2; ++n) _Pragma("unroll") for (int k = 0; k < 2; ++k) \
;         acc[ai][bj][m][n] = __builtin_amdgcn_mfma_f32_16x16x32_bf16(Bt[n][k], At[m][k], acc[ai][bj][m][n], 0, 0, 0); __builtin_amdgcn_s_setprio(0); } while (0)
; #define PG8_WAIT_V(n) asm volatile("s_waitcnt vmcnt(" #n ")" ::: "memory")
; #define PG8_WAIT_L(n) asm volatile("s_waitcnt lgkmcnt(" #n ")" ::: "memory")
; #define PG8_BAR __builtin_amdgcn_s_barrier()
; #define PG8_SCHED __builtin_amdgcn_sched_barrier(0)
; template <class Epi, class Sched, bool ALIGN_EPI = false, bool SP2 = false, bool RS = false, bool BPRE = false>
; __device__ __forceinline__ void gemm_phase(PG8_LAS unsigned char* lds, const Gemm g, const Sched& S, const Epi& E, const float* rs_ss = nullptr, PG8_LAS float* rs_tab = nullptr) {
;     ...
;             PG8_LDB(B0, 0, 0); PG8_LDB(B1, 0, 1); PG8_SCHED; PG8_LDA(At, 0, 0); PG8_STAGE(PG8_SA(1, 1), a1 + hstep, voffA);
;             PG8_WAIT_V(8); PG8_WAIT_L(0); PG8_BAR; PG8_MMA(0, 0, At, B0); PG8_MMA(0, 1, At, B1); PG8_BAR; PG8_SCHED;
;             PG8_LDA(At, 0, 1); PG8_STAGE(PG8_SB(0, 0), b2, voffB); PG8_STAGE(PG8_SB(0, 1), b2 + hstep, voffB); PG8_STAGE(PG8_SA(0, 0), a2, voffA);
;             PG8_WAIT_V(8); PG8_WAIT_L(0); PG8_BAR; PG8_MMA(1, 0, At, B0); PG8_MMA(1, 1, At, B1); PG8_BAR; PG8_SCHED;
	s_setprio 1
	s_waitcnt lgkmcnt(0)
	v_mfma_f32_16x16x32_bf16 v[126:129], v[130:133], v[186:189], v[126:129]
	v_mfma_f32_16x16x32_bf16 v[126:129], v[134:137], v[190:193], v[126:129]
	v_mfma_f32_16x16x32_bf16 v[122:125], v[156:159], v[190:193], v[122:125]
	v_mfma_f32_16x16x32_bf16 v[122:125], v[152:155], v[186:189], v[122:125]
	v_mfma_f32_16x16x32_bf16 v[106:109], v[152:155], v[194:197], v[106:109]
	v_mfma_f32_16x16x32_bf16 v[106:109], v[156:159], v[198:201], v[106:109]
	v_mfma_f32_16x16x32_bf16 v[110:113], v[134:137], v[198:201], v[110:113]
	v_mfma_f32_16x16x32_bf16 v[110:113], v[130:133], v[194:197], v[110:113]
	v_mfma_f32_16x16x32_bf16 v[94:97], v[130:133], v[202:205], v[94:97]
	v_mfma_f32_16x16x32_bf16 v[94:97], v[134:137], v[206:209], v[94:97]
	v_mfma_f32_16x16x32_bf16 v[90:93], v[156:159], v[206:209], v[90:93]
	v_mfma_f32_16x16x32_bf16 v[90:93], v[152:155], v[202:205], v[90:93]
	v_mfma_f32_16x16x32_bf16 v[74:77], v[152:155], v[210:213], v[74:77]
	v_mfma_f32_16x16x32_bf16 v[74:77], v[156:159], v[214:217], v[74:77]
	v_mfma_f32_16x16x32_bf16 v[78:81], v[134:137], v[214:217], v[78:81]
	v_mfma_f32_16x16x32_bf16 v[78:81], v[130:133], v[210:213], v[78:81]
	v_mfma_f32_16x16x32_bf16 v[70:73], v[166:169], v[210:213], v[70:73]
	v_mfma_f32_16x16x32_bf16 v[70:73], v[170:173], v[214:217], v[70:73]
	v_mfma_f32_16x16x32_bf16 v[66:69], v[182:185], v[214:217], v[66:69]
	v_mfma_f32_16x16x32_bf16 v[66:69], v[174:177], v[210:213], v[66:69]
	v_mfma_f32_16x16x32_bf16 v[82:85], v[174:177], v[202:205], v[82:85]
	v_mfma_f32_16x16x32_bf16 v[82:85], v[182:185], v[206:209], v[82:85]
	v_mfma_f32_16x16x32_bf16 v[86:89], v[170:173], v[206:209], v[86:89]
	v_mfma_f32_16x16x32_bf16 v[86:89], v[166:169], v[202:205], v[86:89]
	v_mfma_f32_16x16x32_bf16 v[102:105], v[166:169], v[194:197], v[102:105]
	v_mfma_f32_16x16x32_bf16 v[102:105], v[170:173], v[198:201], v[102:105]
	v_mfma_f32_16x16x32_bf16 v[98:101], v[182:185], v[198:201], v[98:101]
	v_mfma_f32_16x16x32_bf16 v[98:101], v[174:177], v[194:197], v[98:101]
	v_mfma_f32_16x16x32_bf16 v[114:117], v[174:177], v[186:189], v[114:117]
	v_mfma_f32_16x16x32_bf16 v[114:117], v[182:185], v[190:193], v[114:117]
	v_mfma_f32_16x16x32_bf16 v[118:121], v[170:173], v[190:193], v[118:121]
	v_mfma_f32_16x16x32_bf16 v[118:121], v[166:169], v[186:189], v[118:121]
	s_setprio 0
	s_barrier
	s_add_i32 s90, s83, s15
	v_lshl_add_u64 v[178:179], s[60:61], 0, v[138:139]
	s_mov_b32 m0, s90
	ds_read_b128 v[186:189], v163 offset:16384
	ds_read_b128 v[190:193], v163 offset:17408
	ds_read_b128 v[194:197], v163 offset:18432
	ds_read_b128 v[198:201], v163 offset:19456
	ds_read_b128 v[202:205], v163 offset:20480
	ds_read_b128 v[206:209], v163 offset:21504
	ds_read_b128 v[210:213], v163 offset:22528
	ds_read_b128 v[214:217], v163 offset:23552
	global_load_lds_dwordx4 v[178:179], off
	s_add_i32 m0, s90, 0x2000
	s_add_u32 s90, s60, 0x80000
	v_lshl_add_u64 v[178:179], s[60:61], 0, v[140:141]
	s_addc_u32 s91, s61, 0
	s_add_i32 s92, s86, s15
	global_load_lds_dwordx4 v[178:179], off
	v_lshl_add_u64 v[178:179], s[90:91], 0, v[138:139]
	s_mov_b32 m0, s92
	s_nop 0
	global_load_lds_dwordx4 v[178:179], off
	v_lshl_add_u64 v[178:179], s[90:91], 0, v[140:141]
	s_add_i32 m0, s92, 0x2000
	s_nop 0
	global_load_lds_dwordx4 v[178:179], off
	v_lshl_add_u64 v[178:179], s[70:71], 0, v[138:139]
	s_mov_b32 m0, s72
	s_nop 0
	global_load_lds_dwordx4 v[178:179], off
	v_lshl_add_u64 v[178:179], s[70:71], 0, v[140:141]
	s_mov_b32 m0, s73
	s_nop 0
	global_load_lds_dwordx4 v[178:179], off
	s_waitcnt vmcnt(8)
	s_waitcnt lgkmcnt(0)
	s_barrier
	s_setprio 1
	s_waitcnt lgkmcnt(0)
	v_mfma_f32_16x16x32_bf16 v[62:65], v[130:133], v[186:189], v[62:65]
	v_mfma_f32_16x16x32_bf16 v[62:65], v[134:137], v[190:193], v[62:65]
	v_mfma_f32_16x16x32_bf16 v[58:61], v[156:159], v[190:193], v[58:61]
	v_mfma_f32_16x16x32_bf16 v[58:61], v[152:155], v[186:189], v[58:61]
	v_mfma_f32_16x16x32_bf16 v[42:45], v[152:155], v[194:197], v[42:45]
	v_mfma_f32_16x16x32_bf16 v[42:45], v[156:159], v[198:201], v[42:45]
	v_mfma_f32_16x16x32_bf16 v[46:49], v[134:137], v[198:201], v[46:49]
	v_mfma_f32_16x16x32_bf16 v[46:49], v[130:133], v[194:197], v[46:49]
	v_mfma_f32_16x16x32_bf16 v[30:33], v[130:133], v[202:205], v[30:33]
	v_mfma_f32_16x16x32_bf16 v[30:33], v[134:137], v[206:209], v[30:33]
	v_mfma_f32_16x16x32_bf16 v[26:29], v[156:159], v[206:209], v[26:29]
	v_mfma_f32_16x16x32_bf16 v[26:29], v[152:155], v[202:205], v[26:29]
	v_mfma_f32_16x16x32_bf16 v[10:13], v[152:155], v[210:213], v[10:13]
	v_mfma_f32_16x16x32_bf16 v[10:13], v[156:159], v[214:217], v[10:13]
	v_mfma_f32_16x16x32_bf16 v[14:17], v[134:137], v[214:217], v[14:17]
	v_mfma_f32_16x16x32_bf16 v[14:17], v[130:133], v[210:213], v[14:17]
	v_mfma_f32_16x16x32_bf16 v[6:9], v[166:169], v[210:213], v[6:9]
	v_mfma_f32_16x16x32_bf16 v[6:9], v[170:173], v[214:217], v[6:9]
	v_mfma_f32_16x16x32_bf16 v[2:5], v[182:185], v[214:217], v[2:5]
	v_mfma_f32_16x16x32_bf16 v[2:5], v[174:177], v[210:213], v[2:5]
	v_mfma_f32_16x16x32_bf16 v[18:21], v[174:177], v[202:205], v[18:21]
	v_mfma_f32_16x16x32_bf16 v[18:21], v[182:185], v[206:209], v[18:21]
	v_mfma_f32_16x16x32_bf16 v[22:25], v[170:173], v[206:209], v[22:25]
	v_mfma_f32_16x16x32_bf16 v[22:25], v[166:169], v[202:205], v[22:25]
	v_mfma_f32_16x16x32_bf16 v[38:41], v[166:169], v[194:197], v[38:41]
	v_mfma_f32_16x16x32_bf16 v[38:41], v[170:173], v[198:201], v[38:41]
	v_mfma_f32_16x16x32_bf16 v[34:37], v[182:185], v[198:201], v[34:37]
	v_mfma_f32_16x16x32_bf16 v[34:37], v[174:177], v[194:197], v[34:37]
	v_mfma_f32_16x16x32_bf16 v[50:53], v[174:177], v[186:189], v[50:53]
	v_mfma_f32_16x16x32_bf16 v[50:53], v[182:185], v[190:193], v[50:53]
	v_mfma_f32_16x16x32_bf16 v[54:57], v[170:173], v[190:193], v[54:57]
	v_mfma_f32_16x16x32_bf16 v[54:57], v[166:169], v[186:189], v[54:57]
	s_setprio 0
	s_barrier
; #define PG8_STAGE(bufoff, gbase, voff) do { _Pragma("unroll") for (int _i = 0; _i < 2; ++_i) \
;         __builtin_amdgcn_global_load_lds((const unsigned*)((const char*)(gbase) + (voff)[_i]), (PG8_LAS unsigned*)(lds + (bufoff) + ldsw + _i * 8192), 16, 0, 0); } while (0)
; #define PG8_LDA(dst, b, h) do { _Pragma("unroll") for (int m = 0; m < 4; ++m) _Pragma("unroll") for (int k = 0; k < 2; ++k) dst[m][k] = *(const PG8_LAS bf16x8*)(lds + PG8_SA(b, h) + aoff + m * 2048 + k * 1024); } while (0)
; #define PG8_LDB(dst, b, h) do { _Pragma("unroll") for (int n = 0; n < 2; ++n) _Pragma("unroll") for (int k = 0; k < 2; ++k) dst[n][k] = *(const PG8_LAS bf16x8*)(lds + PG8_SB(b, h) + boff + n * 2048 + k * 1024); } while (0)
; #define PG8_MMA(ai, bj, At, Bt) do { __builtin_amdgcn_s_setprio(1); _Pragma("unroll") for (int m = 0; m < 4; ++m) _Pragma("unroll") for (int n = 0; n < 2; ++n) _Pragma("unroll") for (int k = 0; k < 2; ++k) \
;         acc[ai][bj][m][n] = __builtin_amdgcn_mfma_f32_16x16x32_bf16(Bt[n][k], At[m][k], acc[ai][bj][m][n], 0, 0, 0); __builtin_amdgcn_s_setprio(0); } while (0)
; #define PG8_WAIT_V(n) asm volatile("s_waitcnt vmcnt(" #n ")" ::: "memory")
; #define PG8_WAIT_L(n) asm volatile("s_waitcnt lgkmcnt(" #n ")" ::: "memory")
; #define PG8_BAR __builtin_amdgcn_s_barrier()
; #define PG8_SCHED __builtin_amdgcn_sched_barrier(0)
; template <class Epi, class Sched, bool ALIGN_EPI = false, bool SP2 = false, bool RS = false, bool BPRE = false>
; __device__ __forceinline__ void gemm_phase(PG8_LAS unsigned char* lds, const Gemm g, const Sched& S, const Epi& E, const float* rs_ss = nullptr, PG8_LAS float* rs_tab = nullptr) {
;     ...
;             PG8_LDB(B0, 1, 0); PG8_LDB(B1, 1, 1); PG8_SCHED; PG8_LDA(At, 1, 0); PG8_STAGE(PG8_SA(0, 1), a2 + hstep, voffA);
;             PG8_WAIT_V(8); PG8_WAIT_L(0); PG8_BAR; PG8_MMA(0, 0, At, B0); PG8_MMA(0, 1, At, B1); PG8_BAR; PG8_SCHED;
	s_add_i32 s90, 0, 0x18000
	v_add_u32_e32 v143, s90, v160
	s_add_i32 s91, 0, 0x1c000
	ds_read_b128 v[130:133], v143
	ds_read_b128 v[134:137], v143 offset:1024
	ds_read_b128 v[152:155], v143 offset:2048
	ds_read_b128 v[156:159], v143 offset:3072
	v_add_u32_e32 v143, s91, v160
	ds_read_b128 v[166:169], v143
	ds_read_b128 v[170:173], v143 offset:1024
	ds_read_b128 v[174:177], v143 offset:2048
	ds_read_b128 v[182:185], v143 offset:3072
	s_add_u32 s70, s70, 0x80000
	s_addc_u32 s71, s71, 0
	s_mov_b32 m0, s74
	v_lshl_add_u64 v[178:179], s[70:71], 0, v[138:139]
	ds_read_b128 v[186:189], v163 offset:32768
	ds_read_b128 v[190:193], v163 offset:33792
	ds_read_b128 v[194:197], v163 offset:34816
	ds_read_b128 v[198:201], v163 offset:35840
	ds_read_b128 v[202:205], v163 offset:36864
	ds_read_b128 v[206:209], v163 offset:37888
	ds_read_b128 v[210:213], v163 offset:38912
	ds_read_b128 v[214:217], v163 offset:39936
	global_load_lds_dwordx4 v[178:179], off
	v_lshl_add_u64 v[178:179], s[70:71], 0, v[140:141]
	s_mov_b32 m0, s75
	s_nop 0
	global_load_lds_dwordx4 v[178:179], off
	s_waitcnt vmcnt(8)
	s_waitcnt lgkmcnt(0)
	s_barrier
	s_setprio 1
	s_waitcnt lgkmcnt(0)
	v_mfma_f32_16x16x32_bf16 v[126:129], v[130:133], v[186:189], v[126:129]
	v_mfma_f32_16x16x32_bf16 v[126:129], v[134:137], v[190:193], v[126:129]
	v_mfma_f32_16x16x32_bf16 v[122:125], v[156:159], v[190:193], v[122:125]
	v_mfma_f32_16x16x32_bf16 v[122:125], v[152:155], v[186:189], v[122:125]
	v_mfma_f32_16x16x32_bf16 v[106:109], v[152:155], v[194:197], v[106:109]
	v_mfma_f32_16x16x32_bf16 v[106:109], v[156:159], v[198:201], v[106:109]
	v_mfma_f32_16x16x32_bf16 v[110:113], v[134:137], v[198:201], v[110:113]
	v_mfma_f32_16x16x32_bf16 v[110:113], v[130:133], v[194:197], v[110:113]
	v_mfma_f32_16x16x32_bf16 v[94:97], v[130:133], v[202:205], v[94:97]
	v_mfma_f32_16x16x32_bf16 v[94:97], v[134:137], v[206:209], v[94:97]
	v_mfma_f32_16x16x32_bf16 v[90:93], v[156:159], v[206:209], v[90:93]
	v_mfma_f32_16x16x32_bf16 v[90:93], v[152:155], v[202:205], v[90:93]
	v_mfma_f32_16x16x32_bf16 v[74:77], v[152:155], v[210:213], v[74:77]
	v_mfma_f32_16x16x32_bf16 v[74:77], v[156:159], v[214:217], v[74:77]
	v_mfma_f32_16x16x32_bf16 v[78:81], v[134:137], v[214:217], v[78:81]
	v_mfma_f32_16x16x32_bf16 v[78:81], v[130:133], v[210:213], v[78:81]
	v_mfma_f32_16x16x32_bf16 v[70:73], v[166:169], v[210:213], v[70:73]
	v_mfma_f32_16x16x32_bf16 v[70:73], v[170:173], v[214:217], v[70:73]
	v_mfma_f32_16x16x32_bf16 v[66:69], v[182:185], v[214:217], v[66:69]
	v_mfma_f32_16x16x32_bf16 v[66:69], v[174:177], v[210:213], v[66:69]
	v_mfma_f32_16x16x32_bf16 v[82:85], v[174:177], v[202:205], v[82:85]
	v_mfma_f32_16x16x32_bf16 v[82:85], v[182:185], v[206:209], v[82:85]
	v_mfma_f32_16x16x32_bf16 v[86:89], v[170:173], v[206:209], v[86:89]
	v_mfma_f32_16x16x32_bf16 v[86:89], v[166:169], v[202:205], v[86:89]
	v_mfma_f32_16x16x32_bf16 v[102:105], v[166:169], v[194:197], v[102:105]
	v_mfma_f32_16x16x32_bf16 v[102:105], v[170:173], v[198:201], v[102:105]
	v_mfma_f32_16x16x32_bf16 v[98:101], v[182:185], v[198:201], v[98:101]
	v_mfma_f32_16x16x32_bf16 v[98:101], v[174:177], v[194:197], v[98:101]
	v_mfma_f32_16x16x32_bf16 v[114:117], v[174:177], v[186:189], v[114:117]
	v_mfma_f32_16x16x32_bf16 v[114:117], v[182:185], v[190:193], v[114:117]
	v_mfma_f32_16x16x32_bf16 v[118:121], v[170:173], v[190:193], v[118:121]
	v_mfma_f32_16x16x32_bf16 v[118:121], v[166:169], v[186:189], v[118:121]
	s_setprio 0
	s_barrier
; #define PG8_STAGE(bufoff, gbase, voff) do { _Pragma("unroll") for (int _i = 0; _i < 2; ++_i) \
;         __builtin_amdgcn_global_load_lds((const unsigned*)((const char*)(gbase) + (voff)[_i]), (PG8_LAS unsigned*)(lds + (bufoff) + ldsw + _i * 8192), 16, 0, 0); } while (0)
; #define PG8_LDA(dst, b, h) do { _Pragma("unroll") for (int m = 0; m < 4; ++m) _Pragma("unroll") for (int k = 0; k < 2; ++k) dst[m][k] = *(const PG8_LAS bf16x8*)(lds + PG8_SA(b, h) + aoff + m * 2048 + k * 1024); } while (0)
; #define PG8_MMA(ai, bj, At, Bt) do { __builtin_amdgcn_s_setprio(1); _Pragma("unroll") for (int m = 0; m < 4; ++m) _Pragma("unroll") for (int n = 0; n < 2; ++n) _Pragma("unroll") for (int k = 0; k < 2; ++k) \
;         acc[ai][bj][m][n] = __builtin_amdgcn_mfma_f32_16x16x32_bf16(Bt[n][k], At[m][k], acc[ai][bj][m][n], 0, 0, 0); __builtin_amdgcn_s_setprio(0); } while (0)
; #define PG8_WAIT_V(n) asm volatile("s_waitcnt vmcnt(" #n ")" ::: "memory")
; #define PG8_WAIT_L(n) asm volatile("s_waitcnt lgkmcnt(" #n ")" ::: "memory")
; #define PG8_BAR __builtin_amdgcn_s_barrier()
; #define PG8_SCHED __builtin_amdgcn_sched_barrier(0)
; template <class Epi, class Sched, bool ALIGN_EPI = false, bool SP2 = false, bool RS = false, bool BPRE = false>
; __device__ __forceinline__ void gemm_phase(PG8_LAS unsigned char* lds, const Gemm g, const Sched& S, const Epi& E, const float* rs_ss = nullptr, PG8_LAS float* rs_tab = nullptr) {
;     ...
;         for (int t = 0; t < nt; t += 2) {
;     ...
;             PG8_LDA(At, 1, 1); PG8_STAGE(PG8_SB(1, 0), b3, voffB); PG8_STAGE(PG8_SB(1, 1), b3 + hstep, voffB); PG8_STAGE(PG8_SA(1, 0), a3, voffA);
;             PG8_WAIT_V(8); PG8_WAIT_L(0); PG8_BAR; PG8_MMA(1, 0, At, B0); PG8_MMA(1, 1, At, B1); PG8_BAR; PG8_SCHED;
;     ...
;         if constexpr (ALIGN_EPI) { if (wr == 0) PG8_BAR; }
	s_add_u32 s70, s60, 0x4000
	s_addc_u32 s71, s61, 0
	s_add_i32 s90, s90, s15
	v_lshl_add_u64 v[178:179], s[70:71], 0, v[138:139]
	s_mov_b32 m0, s90
	ds_read_b128 v[186:189], v163 offset:49152
	ds_read_b128 v[190:193], v163 offset:50176
	ds_read_b128 v[194:197], v163 offset:51200
	ds_read_b128 v[198:201], v163 offset:52224
	ds_read_b128 v[202:205], v163 offset:53248
	ds_read_b128 v[206:209], v163 offset:54272
	ds_read_b128 v[210:213], v163 offset:55296
	ds_read_b128 v[214:217], v163 offset:56320
	global_load_lds_dwordx4 v[178:179], off
	s_add_i32 m0, s90, 0x2000
	s_add_u32 s60, s60, 0x84000
	v_lshl_add_u64 v[178:179], s[70:71], 0, v[140:141]
	s_addc_u32 s61, s61, 0
	s_add_i32 s70, s91, s15
	global_load_lds_dwordx4 v[178:179], off
	v_lshl_add_u64 v[178:179], s[60:61], 0, v[138:139]
	s_mov_b32 m0, s70
	s_nop 0
	global_load_lds_dwordx4 v[178:179], off
	v_lshl_add_u64 v[178:179], s[60:61], 0, v[140:141]
	s_add_i32 m0, s70, 0x2000
	s_nop 0
	global_load_lds_dwordx4 v[178:179], off
	v_lshl_add_u64 v[178:179], s[58:59], 0, v[138:139]
	s_mov_b32 m0, s79
	s_nop 0
	global_load_lds_dwordx4 v[178:179], off
	v_lshl_add_u64 v[178:179], s[58:59], 0, v[140:141]
	s_mov_b32 m0, s80
	s_nop 0
	global_load_lds_dwordx4 v[178:179], off
	s_waitcnt vmcnt(8)
	s_waitcnt lgkmcnt(0)
	s_barrier
	s_setprio 1
	s_waitcnt lgkmcnt(0)
	v_mfma_f32_16x16x32_bf16 v[62:65], v[130:133], v[186:189], v[62:65]
	v_mfma_f32_16x16x32_bf16 v[62:65], v[134:137], v[190:193], v[62:65]
	v_mfma_f32_16x16x32_bf16 v[58:61], v[156:159], v[190:193], v[58:61]
	v_mfma_f32_16x16x32_bf16 v[58:61], v[152:155], v[186:189], v[58:61]
	v_mfma_f32_16x16x32_bf16 v[42:45], v[152:155], v[194:197], v[42:45]
	v_mfma_f32_16x16x32_bf16 v[42:45], v[156:159], v[198:201], v[42:45]
	v_mfma_f32_16x16x32_bf16 v[46:49], v[134:137], v[198:201], v[46:49]
	v_mfma_f32_16x16x32_bf16 v[46:49], v[130:133], v[194:197], v[46:49]
	v_mfma_f32_16x16x32_bf16 v[30:33], v[130:133], v[202:205], v[30:33]
	v_mfma_f32_16x16x32_bf16 v[30:33], v[134:137], v[206:209], v[30:33]
	v_mfma_f32_16x16x32_bf16 v[26:29], v[156:159], v[206:209], v[26:29]
	v_mfma_f32_16x16x32_bf16 v[26:29], v[152:155], v[202:205], v[26:29]
	v_mfma_f32_16x16x32_bf16 v[10:13], v[152:155], v[210:213], v[10:13]
	v_mfma_f32_16x16x32_bf16 v[10:13], v[156:159], v[214:217], v[10:13]
	v_mfma_f32_16x16x32_bf16 v[14:17], v[134:137], v[214:217], v[14:17]
	v_mfma_f32_16x16x32_bf16 v[14:17], v[130:133], v[210:213], v[14:17]
	v_mfma_f32_16x16x32_bf16 v[6:9], v[166:169], v[210:213], v[6:9]
	v_mfma_f32_16x16x32_bf16 v[6:9], v[170:173], v[214:217], v[6:9]
	v_mfma_f32_16x16x32_bf16 v[2:5], v[182:185], v[214:217], v[2:5]
	v_mfma_f32_16x16x32_bf16 v[2:5], v[174:177], v[210:213], v[2:5]
	v_mfma_f32_16x16x32_bf16 v[18:21], v[174:177], v[202:205], v[18:21]
	v_mfma_f32_16x16x32_bf16 v[18:21], v[182:185], v[206:209], v[18:21]
	v_mfma_f32_16x16x32_bf16 v[22:25], v[170:173], v[206:209], v[22:25]
	v_mfma_f32_16x16x32_bf16 v[22:25], v[166:169], v[202:205], v[22:25]
	v_mfma_f32_16x16x32_bf16 v[38:41], v[166:169], v[194:197], v[38:41]
	v_mfma_f32_16x16x32_bf16 v[38:41], v[170:173], v[198:201], v[38:41]
	v_mfma_f32_16x16x32_bf16 v[34:37], v[182:185], v[198:201], v[34:37]
	v_mfma_f32_16x16x32_bf16 v[34:37], v[174:177], v[194:197], v[34:37]
	v_mfma_f32_16x16x32_bf16 v[50:53], v[174:177], v[186:189], v[50:53]
	v_mfma_f32_16x16x32_bf16 v[50:53], v[182:185], v[190:193], v[50:53]
	v_mfma_f32_16x16x32_bf16 v[54:57], v[170:173], v[190:193], v[54:57]
	v_mfma_f32_16x16x32_bf16 v[54:57], v[166:169], v[186:189], v[54:57]
	s_setprio 0
	s_barrier
	s_add_i32 s89, s89, 2
	s_add_u32 s56, s56, 0x8000
	s_addc_u32 s57, s57, 0
	s_add_u32 s87, s87, 0x8000
	s_addc_u32 s88, s88, 0
	s_cmp_gt_u32 s89, 29
	s_cbranch_scc0 .LBB0_196
	s_and_b64 vcc, exec, s[12:13]
	s_cbranch_vccz .LBB0_199
	s_barrier

; #define PG8_STAGE(bufoff, gbase, voff) do { _Pragma("unroll") for (int _i = 0; _i < 2; ++_i) \
;         __builtin_amdgcn_global_load_lds((const unsigned*)((const char*)(gbase) + (voff)[_i]), (PG8_LAS unsigned*)(lds + (bufoff) + ldsw + _i * 8192), 16, 0, 0); } while (0)
; #define PG8_LDA(dst, b, h) do { _Pragma("unroll") for (int m = 0; m < 4; ++m) _Pragma("unroll") for (int k = 0; k < 2; ++k) dst[m][k] = *(const PG8_LAS bf16x8*)(lds + PG8_SA(b, h) + aoff + m * 2048 + k * 1024); } while (0)
; #define PG8_LDB(dst, b, h) do { _Pragma("unroll") for (int n = 0; n < 2; ++n) _Pragma("unroll") for (int k = 0; k < 2; ++k) dst[n][k] = *(const PG8_LAS bf16x8*)(lds + PG8_SB(b, h) + boff + n * 2048 + k * 1024); } while (0)
; #define PG8_MMA(ai, bj, At, Bt) do { __builtin_amdgcn_s_setprio(1); _Pragma("unroll") for (int m = 0; m < 4; ++m) _Pragma("unroll") for (int n = 0; n < 2; ++n) _Pragma("unroll") for (int k = 0; k < 2; ++k) \
;         acc[ai][bj][m][n] = __builtin_amdgcn_mfma_f32_16x16x32_bf16(Bt[n][k], At[m][k], acc[ai][bj][m][n], 0, 0, 0); __builtin_amdgcn_s_setprio(0); } while (0)
; template <class Epi, class Sched, bool ALIGN_EPI = false, bool SP2 = false, bool RS = false, bool BPRE = false>
; __device__ __forceinline__ void gemm_phase(PG8_LAS unsigned char* lds, const Gemm g, const Sched& S, const Epi& E, const float* rs_ss = nullptr, PG8_LAS float* rs_tab = nullptr) {
;     ...
;             const char* a1 = cA + (size_t)(t + 1) * kstep;
;             const char* a2 = last ? nA : cA + (size_t)(t + 2) * kstep; const char* b2 = last ? nB : cB + (size_t)(t + 2) * kstep;
;             const char* a3 = a2 + kstep; const char* b3 = b2 + kstep;
;             if (last && has_next) S.a_ready(nxt);
;             if constexpr (SP2) {
;             PG8_LDB(B0, 0, 0); PG8_LDB(B1, 0, 1); PG8_SCHED; PG8_LDA(At, 0, 0); PG8_STAGE(PG8_SA(1, 1), a1 + hstep, voffA);
;             PG8_WAIT_V(8); PG8_WAIT_L(0); PG8_BAR; PG8_MMA(0, 0, At, B0); PG8_MMA(0, 1, At, B1); PG8_BAR; PG8_SCHED;
;             PG8_LDA(At, 0, 1); PG8_STAGE(PG8_SB(0, 0), b2, voffB); PG8_STAGE(PG8_SB(0, 1), b2 + hstep, voffB); PG8_STAGE(PG8_SA(0, 0), a2, voffA);
;             PG8_WAIT_V(8); PG8_WAIT_L(0); PG8_BAR; PG8_MMA(1, 0, At, B0); PG8_MMA(1, 1, At, B1); PG8_BAR; PG8_SCHED;
;     ...
;         if constexpr (!Epi::AFTER_DRAIN) { E(acc, cur, wr, wc, fr, fq, rs_tab + (ui & 1) * 768); S.done(cur); }
.LBB0_751:
	s_bitcmp1_b32 s40, 0
	v_mov_b32_e32 v4, v2
	v_mov_b32_e32 v5, v2
	s_cselect_b32 s6, 0xc00, 0
	s_add_u32 s71, s38, 0x8000
	v_mov_b32_e32 v3, v2
	s_waitcnt lgkmcnt(0)
	s_waitcnt vmcnt(0)
	s_mov_b32 s73, 0
	v_add_u32_e32 v158, s6, v151
	v_lshl_add_u64 v[146:147], s[10:11], 0, v[138:139]
	v_lshl_add_u64 v[148:149], s[10:11], 0, v[140:141]
	s_addc_u32 s72, s39, 0
	s_mov_b64 s[6:7], 0
	s_add_u32 s38, s10, s6
	v_add_u32_e32 v3, s64, v150
	s_addc_u32 s39, s11, s7
	ds_read_b128 v[160:163], v3
	ds_read_b128 v[164:167], v3 offset:1024
	ds_read_b128 v[168:171], v3 offset:2048
	ds_read_b128 v[172:175], v3 offset:3072
	v_add_u32_e32 v3, s65, v150
	s_add_u32 s38, s38, 0x8000
	ds_read_b128 v[176:179], v3
	ds_read_b128 v[180:183], v3 offset:1024
	ds_read_b128 v[184:187], v3 offset:2048
	ds_read_b128 v[188:191], v3 offset:3072
	s_addc_u32 s39, s39, 0
	s_add_u32 s40, s71, s6
	s_addc_u32 s41, s72, s7
	s_cmp_eq_u32 s6, 0xb8000
	s_cselect_b32 s42, s20, s38
	s_cselect_b32 s43, s21, s39
	s_cselect_b32 s40, s36, s40
	s_cselect_b32 s41, s37, s41
	s_add_u32 s38, s42, 0x4000
	s_addc_u32 s39, s43, 0
	v_lshl_add_u64 v[4:5], v[146:147], 0, s[6:7]
	s_add_i32 m0, s55, 0xc000
	ds_read_b128 v[192:195], v154
	ds_read_b128 v[196:199], v154 offset:1024
	ds_read_b128 v[200:203], v154 offset:2048
	ds_read_b128 v[204:207], v154 offset:3072
	ds_read_b128 v[208:211], v154 offset:4096
	ds_read_b128 v[212:215], v154 offset:5120
	ds_read_b128 v[216:219], v154 offset:6144
	ds_read_b128 v[220:223], v154 offset:7168
	global_load_lds_dwordx4 v[4:5], off
	v_lshl_add_u64 v[4:5], v[148:149], 0, s[6:7]
	s_add_i32 m0, s55, 0xe000
	s_nop 0
	global_load_lds_dwordx4 v[4:5], off
	s_waitcnt vmcnt(8)
	s_waitcnt lgkmcnt(0)
	s_barrier
	s_setprio 1
	s_waitcnt lgkmcnt(0)
	v_mfma_f32_16x16x32_bf16 v[130:133], v[160:163], v[192:195], 0
	v_mfma_f32_16x16x32_bf16 v[130:133], v[164:167], v[196:199], v[130:133]
	v_mfma_f32_16x16x32_bf16 v[126:129], v[172:175], v[196:199], 0
	v_mfma_f32_16x16x32_bf16 v[126:129], v[168:171], v[192:195], v[126:129]
	v_mfma_f32_16x16x32_bf16 v[110:113], v[168:171], v[200:203], 0
	v_mfma_f32_16x16x32_bf16 v[110:113], v[172:175], v[204:207], v[110:113]
	v_mfma_f32_16x16x32_bf16 v[114:117], v[164:167], v[204:207], 0
	v_mfma_f32_16x16x32_bf16 v[114:117], v[160:163], v[200:203], v[114:117]
	v_mfma_f32_16x16x32_bf16 v[98:101], v[160:163], v[208:211], 0
	v_mfma_f32_16x16x32_bf16 v[98:101], v[164:167], v[212:215], v[98:101]
	v_mfma_f32_16x16x32_bf16 v[94:97], v[172:175], v[212:215], 0
	v_mfma_f32_16x16x32_bf16 v[94:97], v[168:171], v[208:211], v[94:97]
	v_mfma_f32_16x16x32_bf16 v[78:81], v[168:171], v[216:219], 0
	v_mfma_f32_16x16x32_bf16 v[78:81], v[172:175], v[220:223], v[78:81]
	v_mfma_f32_16x16x32_bf16 v[82:85], v[164:167], v[220:223], 0
	v_mfma_f32_16x16x32_bf16 v[82:85], v[160:163], v[216:219], v[82:85]
	v_mfma_f32_16x16x32_bf16 v[74:77], v[176:179], v[216:219], 0
	v_mfma_f32_16x16x32_bf16 v[74:77], v[180:183], v[220:223], v[74:77]
	v_mfma_f32_16x16x32_bf16 v[70:73], v[188:191], v[220:223], 0
	v_mfma_f32_16x16x32_bf16 v[70:73], v[184:187], v[216:219], v[70:73]
	v_mfma_f32_16x16x32_bf16 v[86:89], v[184:187], v[208:211], 0
	v_mfma_f32_16x16x32_bf16 v[86:89], v[188:191], v[212:215], v[86:89]
	v_mfma_f32_16x16x32_bf16 v[90:93], v[180:183], v[212:215], 0
	v_mfma_f32_16x16x32_bf16 v[90:93], v[176:179], v[208:211], v[90:93]
	v_mfma_f32_16x16x32_bf16 v[106:109], v[176:179], v[200:203], 0
	v_mfma_f32_16x16x32_bf16 v[106:109], v[180:183], v[204:207], v[106:109]
	v_mfma_f32_16x16x32_bf16 v[102:105], v[188:191], v[204:207], 0
	v_mfma_f32_16x16x32_bf16 v[102:105], v[184:187], v[200:203], v[102:105]
	v_mfma_f32_16x16x32_bf16 v[118:121], v[184:187], v[192:195], 0
	v_mfma_f32_16x16x32_bf16 v[118:121], v[188:191], v[196:199], v[118:121]
	v_mfma_f32_16x16x32_bf16 v[122:125], v[180:183], v[196:199], 0
	v_mfma_f32_16x16x32_bf16 v[122:125], v[176:179], v[192:195], v[122:125]
	s_setprio 0
	s_barrier
	s_add_i32 s74, s64, s54
	v_lshl_add_u64 v[4:5], s[40:41], 0, v[134:135]
	s_mov_b32 m0, s74
	ds_read_b128 v[192:195], v154 offset:16384
	ds_read_b128 v[196:199], v154 offset:17408
	ds_read_b128 v[200:203], v154 offset:18432
	ds_read_b128 v[204:207], v154 offset:19456
	ds_read_b128 v[208:211], v154 offset:20480
	ds_read_b128 v[212:215], v154 offset:21504
	ds_read_b128 v[216:219], v154 offset:22528
	ds_read_b128 v[220:223], v154 offset:23552
	global_load_lds_dwordx4 v[4:5], off
	s_add_i32 m0, s74, 0x2000
	s_add_u32 s74, s40, 0xc0000
	v_lshl_add_u64 v[4:5], s[40:41], 0, v[136:137]
	s_addc_u32 s75, s41, 0
	s_add_i32 s76, s65, s54
	global_load_lds_dwordx4 v[4:5], off
	v_lshl_add_u64 v[4:5], s[74:75], 0, v[134:135]
	s_mov_b32 m0, s76
	s_nop 0
	global_load_lds_dwordx4 v[4:5], off
	v_lshl_add_u64 v[4:5], s[74:75], 0, v[136:137]
	s_add_i32 m0, s76, 0x2000
	s_nop 0
	global_load_lds_dwordx4 v[4:5], off
	v_lshl_add_u64 v[4:5], s[42:43], 0, v[134:135]
	s_mov_b32 m0, s55
	s_nop 0
	global_load_lds_dwordx4 v[4:5], off
	v_lshl_add_u64 v[4:5], s[42:43], 0, v[136:137]
	s_mov_b32 m0, s56
	s_nop 0
	global_load_lds_dwordx4 v[4:5], off
	s_waitcnt vmcnt(8)
	s_waitcnt lgkmcnt(0)
	s_barrier
; #define PG8_STAGE(bufoff, gbase, voff) do { _Pragma("unroll") for (int _i = 0; _i < 2; ++_i) \
;         __builtin_amdgcn_global_load_lds((const unsigned*)((const char*)(gbase) + (voff)[_i]), (PG8_LAS unsigned*)(lds + (bufoff) + ldsw + _i * 8192), 16, 0, 0); } while (0)
; #define PG8_LDA(dst, b, h) do { _Pragma("unroll") for (int m = 0; m < 4; ++m) _Pragma("unroll") for (int k = 0; k < 2; ++k) dst[m][k] = *(const PG8_LAS bf16x8*)(lds + PG8_SA(b, h) + aoff + m * 2048 + k * 1024); } while (0)
; #define PG8_LDB(dst, b, h) do { _Pragma("unroll") for (int n = 0; n < 2; ++n) _Pragma("unroll") for (int k = 0; k < 2; ++k) dst[n][k] = *(const PG8_LAS bf16x8*)(lds + PG8_SB(b, h) + boff + n * 2048 + k * 1024); } while (0)
; #define PG8_MMA(ai, bj, At, Bt) do { __builtin_amdgcn_s_setprio(1); _Pragma("unroll") for (int m = 0; m < 4; ++m) _Pragma("unroll") for (int n = 0; n < 2; ++n) _Pragma("unroll") for (int k = 0; k < 2; ++k) \
;         acc[ai][bj][m][n] = __builtin_amdgcn_mfma_f32_16x16x32_bf16(Bt[n][k], At[m][k], acc[ai][bj][m][n], 0, 0, 0); __builtin_amdgcn_s_setprio(0); } while (0)
; #define PG8_WAIT_V(n) asm volatile("s_waitcnt vmcnt(" #n ")" ::: "memory")
; #define PG8_WAIT_L(n) asm volatile("s_waitcnt lgkmcnt(" #n ")" ::: "memory")
; #define PG8_BAR __builtin_amdgcn_s_barrier()
; #define PG8_SCHED __builtin_amdgcn_sched_barrier(0)
; template <class Epi, class Sched, bool ALIGN_EPI = false, bool SP2 = false, bool RS = false, bool BPRE = false>
; __device__ __forceinline__ void gemm_phase(PG8_LAS unsigned char* lds, const Gemm g, const Sched& S, const Epi& E, const float* rs_ss = nullptr, PG8_LAS float* rs_tab = nullptr) {
;     ...
;             PG8_WAIT_V(8); PG8_WAIT_L(0); PG8_BAR; PG8_MMA(1, 0, At, B0); PG8_MMA(1, 1, At, B1); PG8_BAR; PG8_SCHED;
;             PG8_LDB(B0, 1, 0); PG8_LDB(B1, 1, 1); PG8_SCHED; PG8_LDA(At, 1, 0); PG8_STAGE(PG8_SA(0, 1), a2 + hstep, voffA);
;             PG8_WAIT_V(8); PG8_WAIT_L(0); PG8_BAR; PG8_MMA(0, 0, At, B0); PG8_MMA(0, 1, At, B1); PG8_BAR; PG8_SCHED;
	s_setprio 1
	s_waitcnt lgkmcnt(0)
	v_mfma_f32_16x16x32_bf16 v[66:69], v[160:163], v[192:195], 0
	v_mfma_f32_16x16x32_bf16 v[66:69], v[164:167], v[196:199], v[66:69]
	v_mfma_f32_16x16x32_bf16 v[62:65], v[172:175], v[196:199], 0
	v_mfma_f32_16x16x32_bf16 v[62:65], v[168:171], v[192:195], v[62:65]
	v_mfma_f32_16x16x32_bf16 v[46:49], v[168:171], v[200:203], 0
	v_mfma_f32_16x16x32_bf16 v[46:49], v[172:175], v[204:207], v[46:49]
	v_mfma_f32_16x16x32_bf16 v[50:53], v[164:167], v[204:207], 0
	v_mfma_f32_16x16x32_bf16 v[50:53], v[160:163], v[200:203], v[50:53]
	v_mfma_f32_16x16x32_bf16 v[34:37], v[160:163], v[208:211], 0
	v_mfma_f32_16x16x32_bf16 v[34:37], v[164:167], v[212:215], v[34:37]
	v_mfma_f32_16x16x32_bf16 v[30:33], v[172:175], v[212:215], 0
	v_mfma_f32_16x16x32_bf16 v[30:33], v[168:171], v[208:211], v[30:33]
	v_mfma_f32_16x16x32_bf16 v[14:17], v[168:171], v[216:219], 0
	v_mfma_f32_16x16x32_bf16 v[14:17], v[172:175], v[220:223], v[14:17]
	v_mfma_f32_16x16x32_bf16 v[18:21], v[164:167], v[220:223], 0
	v_mfma_f32_16x16x32_bf16 v[18:21], v[160:163], v[216:219], v[18:21]
	v_mfma_f32_16x16x32_bf16 v[10:13], v[176:179], v[216:219], 0
	v_mfma_f32_16x16x32_bf16 v[10:13], v[180:183], v[220:223], v[10:13]
	v_mfma_f32_16x16x32_bf16 v[4:7], v[188:191], v[220:223], 0
	v_mfma_f32_16x16x32_bf16 v[4:7], v[184:187], v[216:219], v[4:7]
	v_mfma_f32_16x16x32_bf16 v[22:25], v[184:187], v[208:211], 0
	v_mfma_f32_16x16x32_bf16 v[22:25], v[188:191], v[212:215], v[22:25]
	v_mfma_f32_16x16x32_bf16 v[26:29], v[180:183], v[212:215], 0
	v_mfma_f32_16x16x32_bf16 v[26:29], v[176:179], v[208:211], v[26:29]
	v_mfma_f32_16x16x32_bf16 v[42:45], v[176:179], v[200:203], 0
	v_mfma_f32_16x16x32_bf16 v[42:45], v[180:183], v[204:207], v[42:45]
	v_mfma_f32_16x16x32_bf16 v[38:41], v[188:191], v[204:207], 0
	v_mfma_f32_16x16x32_bf16 v[38:41], v[184:187], v[200:203], v[38:41]
	v_mfma_f32_16x16x32_bf16 v[54:57], v[184:187], v[192:195], 0
	v_mfma_f32_16x16x32_bf16 v[54:57], v[188:191], v[196:199], v[54:57]
	v_mfma_f32_16x16x32_bf16 v[58:61], v[180:183], v[196:199], 0
	v_mfma_f32_16x16x32_bf16 v[58:61], v[176:179], v[192:195], v[58:61]
	s_setprio 0
	s_barrier
	s_add_i32 s74, 0, 0x18000
	v_add_u32_e32 v3, s74, v150
	s_add_i32 s75, 0, 0x1c000
	ds_read_b128 v[160:163], v3
	ds_read_b128 v[164:167], v3 offset:1024
	ds_read_b128 v[168:171], v3 offset:2048
	ds_read_b128 v[172:175], v3 offset:3072
	v_add_u32_e32 v3, s75, v150
	ds_read_b128 v[176:179], v3
	ds_read_b128 v[180:183], v3 offset:1024
	ds_read_b128 v[184:187], v3 offset:2048
	ds_read_b128 v[188:191], v3 offset:3072
	s_add_u32 s42, s42, 0xc0000
	s_addc_u32 s43, s43, 0
	s_mov_b32 m0, s57
	v_lshl_add_u64 v[8:9], s[42:43], 0, v[134:135]
	ds_read_b128 v[192:195], v154 offset:32768
	ds_read_b128 v[196:199], v154 offset:33792
	ds_read_b128 v[200:203], v154 offset:34816
	ds_read_b128 v[204:207], v154 offset:35840
	ds_read_b128 v[208:211], v154 offset:36864
	ds_read_b128 v[212:215], v154 offset:37888
	ds_read_b128 v[216:219], v154 offset:38912
	ds_read_b128 v[220:223], v154 offset:39936
	global_load_lds_dwordx4 v[8:9], off
	v_lshl_add_u64 v[8:9], s[42:43], 0, v[136:137]
	s_mov_b32 m0, s58
	s_nop 0
	global_load_lds_dwordx4 v[8:9], off
	s_waitcnt vmcnt(8)
	s_waitcnt lgkmcnt(0)
	s_barrier
	s_setprio 1
	s_waitcnt lgkmcnt(0)
	v_mfma_f32_16x16x32_bf16 v[130:133], v[160:163], v[192:195], v[130:133]
	v_mfma_f32_16x16x32_bf16 v[130:133], v[164:167], v[196:199], v[130:133]
	v_mfma_f32_16x16x32_bf16 v[126:129], v[172:175], v[196:199], v[126:129]
	v_mfma_f32_16x16x32_bf16 v[126:129], v[168:171], v[192:195], v[126:129]
	v_mfma_f32_16x16x32_bf16 v[110:113], v[168:171], v[200:203], v[110:113]
	v_mfma_f32_16x16x32_bf16 v[110:113], v[172:175], v[204:207], v[110:113]
	v_mfma_f32_16x16x32_bf16 v[114:117], v[164:167], v[204:207], v[114:117]
	v_mfma_f32_16x16x32_bf16 v[114:117], v[160:163], v[200:203], v[114:117]
	v_mfma_f32_16x16x32_bf16 v[98:101], v[160:163], v[208:211], v[98:101]
	v_mfma_f32_16x16x32_bf16 v[98:101], v[164:167], v[212:215], v[98:101]
	v_mfma_f32_16x16x32_bf16 v[94:97], v[172:175], v[212:215], v[94:97]
	v_mfma_f32_16x16x32_bf16 v[94:97], v[168:171], v[208:211], v[94:97]
	v_mfma_f32_16x16x32_bf16 v[78:81], v[168:171], v[216:219], v[78:81]
	v_mfma_f32_16x16x32_bf16 v[78:81], v[172:175], v[220:223], v[78:81]
	v_mfma_f32_16x16x32_bf16 v[82:85], v[164:167], v[220:223], v[82:85]
	v_mfma_f32_16x16x32_bf16 v[82:85], v[160:163], v[216:219], v[82:85]
	v_mfma_f32_16x16x32_bf16 v[74:77], v[176:179], v[216:219], v[74:77]
	v_mfma_f32_16x16x32_bf16 v[74:77], v[180:183], v[220:223], v[74:77]
	v_mfma_f32_16x16x32_bf16 v[70:73], v[188:191], v[220:223], v[70:73]
	v_mfma_f32_16x16x32_bf16 v[70:73], v[184:187], v[216:219], v[70:73]
	v_mfma_f32_16x16x32_bf16 v[86:89], v[184:187], v[208:211], v[86:89]
	v_mfma_f32_16x16x32_bf16 v[86:89], v[188:191], v[212:215], v[86:89]
	v_mfma_f32_16x16x32_bf16 v[90:93], v[180:183], v[212:215], v[90:93]
	v_mfma_f32_16x16x32_bf16 v[90:93], v[176:179], v[208:211], v[90:93]
	v_mfma_f32_16x16x32_bf16 v[106:109], v[176:179], v[200:203], v[106:109]
	v_mfma_f32_16x16x32_bf16 v[106:109], v[180:183], v[204:207], v[106:109]
	v_mfma_f32_16x16x32_bf16 v[102:105], v[188:191], v[204:207], v[102:105]
	v_mfma_f32_16x16x32_bf16 v[102:105], v[184:187], v[200:203], v[102:105]
	v_mfma_f32_16x16x32_bf16 v[118:121], v[184:187], v[192:195], v[118:121]
	v_mfma_f32_16x16x32_bf16 v[118:121], v[188:191], v[196:199], v[118:121]
	v_mfma_f32_16x16x32_bf16 v[122:125], v[180:183], v[196:199], v[122:125]
	v_mfma_f32_16x16x32_bf16 v[122:125], v[176:179], v[192:195], v[122:125]
	s_setprio 0
	s_barrier
; #define PG8_STAGE(bufoff, gbase, voff) do { _Pragma("unroll") for (int _i = 0; _i < 2; ++_i) \
;         __builtin_amdgcn_global_load_lds((const unsigned*)((const char*)(gbase) + (voff)[_i]), (PG8_LAS unsigned*)(lds + (bufoff) + ldsw + _i * 8192), 16, 0, 0); } while (0)
; #define PG8_LDA(dst, b, h) do { _Pragma("unroll") for (int m = 0; m < 4; ++m) _Pragma("unroll") for (int k = 0; k < 2; ++k) dst[m][k] = *(const PG8_LAS bf16x8*)(lds + PG8_SA(b, h) + aoff + m * 2048 + k * 1024); } while (0)
; #define PG8_LDB(dst, b, h) do { _Pragma("unroll") for (int n = 0; n < 2; ++n) _Pragma("unroll") for (int k = 0; k < 2; ++k) dst[n][k] = *(const PG8_LAS bf16x8*)(lds + PG8_SB(b, h) + boff + n * 2048 + k * 1024); } while (0)
; #define PG8_MMA(ai, bj, At, Bt) do { __builtin_amdgcn_s_setprio(1); _Pragma("unroll") for (int m = 0; m < 4; ++m) _Pragma("unroll") for (int n = 0; n < 2; ++n) _Pragma("unroll") for (int k = 0; k < 2; ++k) \
;         acc[ai][bj][m][n] = __builtin_amdgcn_mfma_f32_16x16x32_bf16(Bt[n][k], At[m][k], acc[ai][bj][m][n], 0, 0, 0); __builtin_amdgcn_s_setprio(0); } while (0)
; #define PG8_WAIT_V(n) asm volatile("s_waitcnt vmcnt(" #n ")" ::: "memory")
; #define PG8_WAIT_L(n) asm volatile("s_waitcnt lgkmcnt(" #n ")" ::: "memory")
; #define PG8_BAR __builtin_amdgcn_s_barrier()
; #define PG8_SCHED __builtin_amdgcn_sched_barrier(0)
; template <class Epi, class Sched, bool ALIGN_EPI = false, bool SP2 = false, bool RS = false, bool BPRE = false>
; __device__ __forceinline__ void gemm_phase(PG8_LAS unsigned char* lds, const Gemm g, const Sched& S, const Epi& E, const float* rs_ss = nullptr, PG8_LAS float* rs_tab = nullptr) {
;     ...
;         for (int t = 0; t < nt; t += 2) {
;     ...
;             PG8_LDB(B0, 0, 0); PG8_LDB(B1, 0, 1); PG8_SCHED; PG8_LDA(At, 0, 0); PG8_STAGE(PG8_SA(1, 1), a1 + hstep, voffA);
;             PG8_WAIT_V(8); PG8_WAIT_L(0); PG8_BAR; PG8_MMA(0, 0, At, B0); PG8_MMA(0, 1, At, B1); PG8_BAR; PG8_SCHED;
;     ...
;             PG8_LDA(At, 1, 1); PG8_STAGE(PG8_SB(1, 0), b3, voffB); PG8_STAGE(PG8_SB(1, 1), b3 + hstep, voffB); PG8_STAGE(PG8_SA(1, 0), a3, voffA);
;             PG8_WAIT_V(8); PG8_WAIT_L(0); PG8_BAR; PG8_MMA(1, 0, At, B0); PG8_MMA(1, 1, At, B1); PG8_BAR; PG8_SCHED;
	s_add_u32 s42, s40, 0x4000
	s_addc_u32 s43, s41, 0
	s_add_i32 s74, s74, s54
	v_lshl_add_u64 v[8:9], s[42:43], 0, v[134:135]
	s_mov_b32 m0, s74
	ds_read_b128 v[192:195], v154 offset:49152
	ds_read_b128 v[196:199], v154 offset:50176
	ds_read_b128 v[200:203], v154 offset:51200
	ds_read_b128 v[204:207], v154 offset:52224
	ds_read_b128 v[208:211], v154 offset:53248
	ds_read_b128 v[212:215], v154 offset:54272
	ds_read_b128 v[216:219], v154 offset:55296
	ds_read_b128 v[220:223], v154 offset:56320
	global_load_lds_dwordx4 v[8:9], off
	s_add_i32 m0, s74, 0x2000
	s_add_u32 s40, s40, 0xc4000
	v_lshl_add_u64 v[8:9], s[42:43], 0, v[136:137]
	s_addc_u32 s41, s41, 0
	s_add_i32 s42, s75, s54
	global_load_lds_dwordx4 v[8:9], off
	v_lshl_add_u64 v[8:9], s[40:41], 0, v[134:135]
	s_mov_b32 m0, s42
	s_nop 0
	global_load_lds_dwordx4 v[8:9], off
	v_lshl_add_u64 v[8:9], s[40:41], 0, v[136:137]
	s_add_i32 m0, s42, 0x2000
	s_nop 0
	global_load_lds_dwordx4 v[8:9], off
	v_lshl_add_u64 v[8:9], s[38:39], 0, v[134:135]
	s_mov_b32 m0, s60
	s_nop 0
	global_load_lds_dwordx4 v[8:9], off
	v_lshl_add_u64 v[8:9], s[38:39], 0, v[136:137]
	s_mov_b32 m0, s61
	s_nop 0
	global_load_lds_dwordx4 v[8:9], off
	s_waitcnt vmcnt(8)
	s_waitcnt lgkmcnt(0)
	s_barrier
	s_setprio 1
	s_waitcnt lgkmcnt(0)
	v_mfma_f32_16x16x32_bf16 v[66:69], v[160:163], v[192:195], v[66:69]
	v_mfma_f32_16x16x32_bf16 v[66:69], v[164:167], v[196:199], v[66:69]
	v_mfma_f32_16x16x32_bf16 v[62:65], v[172:175], v[196:199], v[62:65]
	v_mfma_f32_16x16x32_bf16 v[62:65], v[168:171], v[192:195], v[62:65]
	v_mfma_f32_16x16x32_bf16 v[46:49], v[168:171], v[200:203], v[46:49]
	v_mfma_f32_16x16x32_bf16 v[46:49], v[172:175], v[204:207], v[46:49]
	v_mfma_f32_16x16x32_bf16 v[50:53], v[164:167], v[204:207], v[50:53]
	v_mfma_f32_16x16x32_bf16 v[50:53], v[160:163], v[200:203], v[50:53]
	v_mfma_f32_16x16x32_bf16 v[34:37], v[160:163], v[208:211], v[34:37]
	v_mfma_f32_16x16x32_bf16 v[34:37], v[164:167], v[212:215], v[34:37]
	v_mfma_f32_16x16x32_bf16 v[30:33], v[172:175], v[212:215], v[30:33]
	v_mfma_f32_16x16x32_bf16 v[30:33], v[168:171], v[208:211], v[30:33]
	v_mfma_f32_16x16x32_bf16 v[14:17], v[168:171], v[216:219], v[14:17]
	v_mfma_f32_16x16x32_bf16 v[14:17], v[172:175], v[220:223], v[14:17]
	v_mfma_f32_16x16x32_bf16 v[18:21], v[164:167], v[220:223], v[18:21]
	v_mfma_f32_16x16x32_bf16 v[18:21], v[160:163], v[216:219], v[18:21]
	v_mfma_f32_16x16x32_bf16 v[58:61], v[176:179], v[192:195], v[58:61]
	v_mfma_f32_16x16x32_bf16 v[58:61], v[180:183], v[196:199], v[58:61]
	v_mfma_f32_16x16x32_bf16 v[54:57], v[188:191], v[196:199], v[54:57]
	v_mfma_f32_16x16x32_bf16 v[54:57], v[184:187], v[192:195], v[54:57]
	v_mfma_f32_16x16x32_bf16 v[38:41], v[184:187], v[200:203], v[38:41]
	v_mfma_f32_16x16x32_bf16 v[38:41], v[188:191], v[204:207], v[38:41]
	v_mfma_f32_16x16x32_bf16 v[42:45], v[180:183], v[204:207], v[42:45]
	v_mfma_f32_16x16x32_bf16 v[42:45], v[176:179], v[200:203], v[42:45]
	v_mfma_f32_16x16x32_bf16 v[26:29], v[176:179], v[208:211], v[26:29]
	v_mfma_f32_16x16x32_bf16 v[26:29], v[180:183], v[212:215], v[26:29]
	v_mfma_f32_16x16x32_bf16 v[22:25], v[188:191], v[212:215], v[22:25]
	v_mfma_f32_16x16x32_bf16 v[22:25], v[184:187], v[208:211], v[22:25]
	v_mfma_f32_16x16x32_bf16 v[8:11], v[176:179], v[216:219], v[10:13]
	v_mfma_f32_16x16x32_bf16 v[10:13], v[180:183], v[220:223], v[8:11]
	v_mfma_f32_16x16x32_bf16 v[4:7], v[188:191], v[220:223], v[4:7]
	v_mfma_f32_16x16x32_bf16 v[6:9], v[184:187], v[216:219], v[4:7]
	s_setprio 0
	s_barrier
	s_add_i32 s38, s73, 2
	s_add_u32 s6, s6, 0x8000
	s_addc_u32 s7, s7, 0
	s_cmp_gt_u32 s73, 45
	s_mov_b32 s73, s38
	s_branch .LBB0_753
.LBB0_752:
	s_add_u32 s38, s10, s6
	v_add_u32_e32 v3, s64, v150
	s_addc_u32 s39, s11, s7
	ds_read_b128 v[160:163], v3
	ds_read_b128 v[164:167], v3 offset:1024
	ds_read_b128 v[168:171], v3 offset:2048
	ds_read_b128 v[172:175], v3 offset:3072
	v_add_u32_e32 v3, s65, v150
	s_add_u32 s38, s38, 0x8000
	ds_read_b128 v[176:179], v3
	ds_read_b128 v[180:183], v3 offset:1024
	ds_read_b128 v[184:187], v3 offset:2048
	ds_read_b128 v[188:191], v3 offset:3072
	s_addc_u32 s39, s39, 0
	s_add_u32 s40, s71, s6
	s_addc_u32 s41, s72, s7
	s_cmp_eq_u32 s6, 0xb8000
	s_cselect_b32 s42, s20, s38
	s_cselect_b32 s43, s21, s39
	s_cselect_b32 s40, s36, s40
	s_cselect_b32 s41, s37, s41
	s_add_u32 s38, s42, 0x4000
	s_addc_u32 s39, s43, 0
	v_lshl_add_u64 v[4:5], v[146:147], 0, s[6:7]
	s_add_i32 m0, s55, 0xc000
	ds_read_b128 v[192:195], v154
	ds_read_b128 v[196:199], v154 offset:1024
	ds_read_b128 v[200:203], v154 offset:2048
	ds_read_b128 v[204:207], v154 offset:3072
	ds_read_b128 v[208:211], v154 offset:4096
	ds_read_b128 v[212:215], v154 offset:5120
	ds_read_b128 v[216:219], v154 offset:6144
	ds_read_b128 v[220:223], v154 offset:7168
	global_load_lds_dwordx4 v[4:5], off
	v_lshl_add_u64 v[4:5], v[148:149], 0, s[6:7]
	s_add_i32 m0, s55, 0xe000
	s_nop 0
	global_load_lds_dwordx4 v[4:5], off
	s_waitcnt vmcnt(8)
	s_waitcnt lgkmcnt(0)
	s_barrier
; #define PG8_STAGE(bufoff, gbase, voff) do { _Pragma("unroll") for (int _i = 0; _i < 2; ++_i) \
;         __builtin_amdgcn_global_load_lds((const unsigned*)((const char*)(gbase) + (voff)[_i]), (PG8_LAS unsigned*)(lds + (bufoff) + ldsw + _i * 8192), 16, 0, 0); } while (0)
; #define PG8_LDA(dst, b, h) do { _Pragma("unroll") for (int m = 0; m < 4; ++m) _Pragma("unroll") for (int k = 0; k < 2; ++k) dst[m][k] = *(const PG8_LAS bf16x8*)(lds + PG8_SA(b, h) + aoff + m * 2048 + k * 1024); } while (0)
; #define PG8_LDB(dst, b, h) do { _Pragma("unroll") for (int n = 0; n < 2; ++n) _Pragma("unroll") for (int k = 0; k < 2; ++k) dst[n][k] = *(const PG8_LAS bf16x8*)(lds + PG8_SB(b, h) + boff + n * 2048 + k * 1024); } while (0)
; #define PG8_MMA(ai, bj, At, Bt) do { __builtin_amdgcn_s_setprio(1); _Pragma("unroll") for (int m = 0; m < 4; ++m) _Pragma("unroll") for (int n = 0; n < 2; ++n) _Pragma("unroll") for (int k = 0; k < 2; ++k) \
;         acc[ai][bj][m][n] = __builtin_amdgcn_mfma_f32_16x16x32_bf16(Bt[n][k], At[m][k], acc[ai][bj][m][n], 0, 0, 0); __builtin_amdgcn_s_setprio(0); } while (0)
; #define PG8_WAIT_V(n) asm volatile("s_waitcnt vmcnt(" #n ")" ::: "memory")
; #define PG8_WAIT_L(n) asm volatile("s_waitcnt lgkmcnt(" #n ")" ::: "memory")
; #define PG8_BAR __builtin_amdgcn_s_barrier()
; #define PG8_SCHED __builtin_amdgcn_sched_barrier(0)
; template <class Epi, class Sched, bool ALIGN_EPI = false, bool SP2 = false, bool RS = false, bool BPRE = false>
; __device__ __forceinline__ void gemm_phase(PG8_LAS unsigned char* lds, const Gemm g, const Sched& S, const Epi& E, const float* rs_ss = nullptr, PG8_LAS float* rs_tab = nullptr) {
;     ...
;             PG8_LDB(B0, 0, 0); PG8_LDB(B1, 0, 1); PG8_SCHED; PG8_LDA(At, 0, 0); PG8_STAGE(PG8_SA(1, 1), a1 + hstep, voffA);
;             PG8_WAIT_V(8); PG8_WAIT_L(0); PG8_BAR; PG8_MMA(0, 0, At, B0); PG8_MMA(0, 1, At, B1); PG8_BAR; PG8_SCHED;
;             PG8_LDA(At, 0, 1); PG8_STAGE(PG8_SB(0, 0), b2, voffB); PG8_STAGE(PG8_SB(0, 1), b2 + hstep, voffB); PG8_STAGE(PG8_SA(0, 0), a2, voffA);
;             PG8_WAIT_V(8); PG8_WAIT_L(0); PG8_BAR; PG8_MMA(1, 0, At, B0); PG8_MMA(1, 1, At, B1); PG8_BAR; PG8_SCHED;
	s_setprio 1
	s_waitcnt lgkmcnt(0)
	v_mfma_f32_16x16x32_bf16 v[130:133], v[160:163], v[192:195], v[130:133]
	v_mfma_f32_16x16x32_bf16 v[130:133], v[164:167], v[196:199], v[130:133]
	v_mfma_f32_16x16x32_bf16 v[126:129], v[172:175], v[196:199], v[126:129]
	v_mfma_f32_16x16x32_bf16 v[126:129], v[168:171], v[192:195], v[126:129]
	v_mfma_f32_16x16x32_bf16 v[110:113], v[168:171], v[200:203], v[110:113]
	v_mfma_f32_16x16x32_bf16 v[110:113], v[172:175], v[204:207], v[110:113]
	v_mfma_f32_16x16x32_bf16 v[114:117], v[164:167], v[204:207], v[114:117]
	v_mfma_f32_16x16x32_bf16 v[114:117], v[160:163], v[200:203], v[114:117]
	v_mfma_f32_16x16x32_bf16 v[98:101], v[160:163], v[208:211], v[98:101]
	v_mfma_f32_16x16x32_bf16 v[98:101], v[164:167], v[212:215], v[98:101]
	v_mfma_f32_16x16x32_bf16 v[94:97], v[172:175], v[212:215], v[94:97]
	v_mfma_f32_16x16x32_bf16 v[94:97], v[168:171], v[208:211], v[94:97]
	v_mfma_f32_16x16x32_bf16 v[78:81], v[168:171], v[216:219], v[78:81]
	v_mfma_f32_16x16x32_bf16 v[78:81], v[172:175], v[220:223], v[78:81]
	v_mfma_f32_16x16x32_bf16 v[82:85], v[164:167], v[220:223], v[82:85]
	v_mfma_f32_16x16x32_bf16 v[82:85], v[160:163], v[216:219], v[82:85]
	v_mfma_f32_16x16x32_bf16 v[74:77], v[176:179], v[216:219], v[74:77]
	v_mfma_f32_16x16x32_bf16 v[74:77], v[180:183], v[220:223], v[74:77]
	v_mfma_f32_16x16x32_bf16 v[70:73], v[188:191], v[220:223], v[70:73]
	v_mfma_f32_16x16x32_bf16 v[70:73], v[184:187], v[216:219], v[70:73]
	v_mfma_f32_16x16x32_bf16 v[86:89], v[184:187], v[208:211], v[86:89]
	v_mfma_f32_16x16x32_bf16 v[86:89], v[188:191], v[212:215], v[86:89]
	v_mfma_f32_16x16x32_bf16 v[90:93], v[180:183], v[212:215], v[90:93]
	v_mfma_f32_16x16x32_bf16 v[90:93], v[176:179], v[208:211], v[90:93]
	v_mfma_f32_16x16x32_bf16 v[106:109], v[176:179], v[200:203], v[106:109]
	v_mfma_f32_16x16x32_bf16 v[106:109], v[180:183], v[204:207], v[106:109]
	v_mfma_f32_16x16x32_bf16 v[102:105], v[188:191], v[204:207], v[102:105]
	v_mfma_f32_16x16x32_bf16 v[102:105], v[184:187], v[200:203], v[102:105]
	v_mfma_f32_16x16x32_bf16 v[118:121], v[184:187], v[192:195], v[118:121]
	v_mfma_f32_16x16x32_bf16 v[118:121], v[188:191], v[196:199], v[118:121]
	v_mfma_f32_16x16x32_bf16 v[122:125], v[180:183], v[196:199], v[122:125]
	v_mfma_f32_16x16x32_bf16 v[122:125], v[176:179], v[192:195], v[122:125]
	s_setprio 0
	s_barrier
	s_add_i32 s74, s64, s54
	v_lshl_add_u64 v[4:5], s[40:41], 0, v[134:135]
	s_mov_b32 m0, s74
	ds_read_b128 v[192:195], v154 offset:16384
	ds_read_b128 v[196:199], v154 offset:17408
	ds_read_b128 v[200:203], v154 offset:18432
	ds_read_b128 v[204:207], v154 offset:19456
	ds_read_b128 v[208:211], v154 offset:20480
	ds_read_b128 v[212:215], v154 offset:21504
	ds_read_b128 v[216:219], v154 offset:22528
	ds_read_b128 v[220:223], v154 offset:23552
	global_load_lds_dwordx4 v[4:5], off
	s_add_i32 m0, s74, 0x2000
	s_add_u32 s74, s40, 0xc0000
	v_lshl_add_u64 v[4:5], s[40:41], 0, v[136:137]
	s_addc_u32 s75, s41, 0
	s_add_i32 s76, s65, s54
	global_load_lds_dwordx4 v[4:5], off
	v_lshl_add_u64 v[4:5], s[74:75], 0, v[134:135]
	s_mov_b32 m0, s76
	s_nop 0
	global_load_lds_dwordx4 v[4:5], off
	v_lshl_add_u64 v[4:5], s[74:75], 0, v[136:137]
	s_add_i32 m0, s76, 0x2000
	s_nop 0
	global_load_lds_dwordx4 v[4:5], off
	v_lshl_add_u64 v[4:5], s[42:43], 0, v[134:135]
	s_mov_b32 m0, s55
	s_nop 0
	global_load_lds_dwordx4 v[4:5], off
	v_lshl_add_u64 v[4:5], s[42:43], 0, v[136:137]
	s_mov_b32 m0, s56
	s_nop 0
	global_load_lds_dwordx4 v[4:5], off
	s_waitcnt vmcnt(8)
	s_waitcnt lgkmcnt(0)
	s_barrier
	s_setprio 1
	s_waitcnt lgkmcnt(0)
	v_mfma_f32_16x16x32_bf16 v[66:69], v[160:163], v[192:195], v[66:69]
	v_mfma_f32_16x16x32_bf16 v[66:69], v[164:167], v[196:199], v[66:69]
	v_mfma_f32_16x16x32_bf16 v[62:65], v[172:175], v[196:199], v[62:65]
	v_mfma_f32_16x16x32_bf16 v[62:65], v[168:171], v[192:195], v[62:65]
	v_mfma_f32_16x16x32_bf16 v[46:49], v[168:171], v[200:203], v[46:49]
	v_mfma_f32_16x16x32_bf16 v[46:49], v[172:175], v[204:207], v[46:49]
	v_mfma_f32_16x16x32_bf16 v[50:53], v[164:167], v[204:207], v[50:53]
	v_mfma_f32_16x16x32_bf16 v[50:53], v[160:163], v[200:203], v[50:53]
	v_mfma_f32_16x16x32_bf16 v[34:37], v[160:163], v[208:211], v[34:37]
	v_mfma_f32_16x16x32_bf16 v[34:37], v[164:167], v[212:215], v[34:37]
	v_mfma_f32_16x16x32_bf16 v[30:33], v[172:175], v[212:215], v[30:33]
	v_mfma_f32_16x16x32_bf16 v[30:33], v[168:171], v[208:211], v[30:33]
	v_mfma_f32_16x16x32_bf16 v[14:17], v[168:171], v[216:219], v[14:17]
	v_mfma_f32_16x16x32_bf16 v[14:17], v[172:175], v[220:223], v[14:17]
	v_mfma_f32_16x16x32_bf16 v[18:21], v[164:167], v[220:223], v[18:21]
	v_mfma_f32_16x16x32_bf16 v[18:21], v[160:163], v[216:219], v[18:21]
	v_mfma_f32_16x16x32_bf16 v[10:13], v[176:179], v[216:219], v[10:13]
	v_mfma_f32_16x16x32_bf16 v[10:13], v[180:183], v[220:223], v[10:13]
	v_mfma_f32_16x16x32_bf16 v[4:7], v[188:191], v[220:223], v[6:9]
	v_mfma_f32_16x16x32_bf16 v[4:7], v[184:187], v[216:219], v[4:7]
	v_mfma_f32_16x16x32_bf16 v[22:25], v[184:187], v[208:211], v[22:25]
	v_mfma_f32_16x16x32_bf16 v[22:25], v[188:191], v[212:215], v[22:25]
	v_mfma_f32_16x16x32_bf16 v[26:29], v[180:183], v[212:215], v[26:29]
	v_mfma_f32_16x16x32_bf16 v[26:29], v[176:179], v[208:211], v[26:29]
	v_mfma_f32_16x16x32_bf16 v[42:45], v[176:179], v[200:203], v[42:45]
	v_mfma_f32_16x16x32_bf16 v[42:45], v[180:183], v[204:207], v[42:45]
	v_mfma_f32_16x16x32_bf16 v[38:41], v[188:191], v[204:207], v[38:41]
	v_mfma_f32_16x16x32_bf16 v[38:41], v[184:187], v[200:203], v[38:41]
	v_mfma_f32_16x16x32_bf16 v[54:57], v[184:187], v[192:195], v[54:57]
	v_mfma_f32_16x16x32_bf16 v[54:57], v[188:191], v[196:199], v[54:57]
	v_mfma_f32_16x16x32_bf16 v[58:61], v[180:183], v[196:199], v[58:61]
	v_mfma_f32_16x16x32_bf16 v[58:61], v[176:179], v[192:195], v[58:61]
	s_setprio 0
	s_barrier
; #define PG8_STAGE(bufoff, gbase, voff) do { _Pragma("unroll") for (int _i = 0; _i < 2; ++_i) \
;         __builtin_amdgcn_global_load_lds((const unsigned*)((const char*)(gbase) + (voff)[_i]), (PG8_LAS unsigned*)(lds + (bufoff) + ldsw + _i * 8192), 16, 0, 0); } while (0)
; #define PG8_LDA(dst, b, h) do { _Pragma("unroll") for (int m = 0; m < 4; ++m) _Pragma("unroll") for (int k = 0; k < 2; ++k) dst[m][k] = *(const PG8_LAS bf16x8*)(lds + PG8_SA(b, h) + aoff + m * 2048 + k * 1024); } while (0)
; #define PG8_LDB(dst, b, h) do { _Pragma("unroll") for (int n = 0; n < 2; ++n) _Pragma("unroll") for (int k = 0; k < 2; ++k) dst[n][k] = *(const PG8_LAS bf16x8*)(lds + PG8_SB(b, h) + boff + n * 2048 + k * 1024); } while (0)
; #define PG8_MMA(ai, bj, At, Bt) do { __builtin_amdgcn_s_setprio(1); _Pragma("unroll") for (int m = 0; m < 4; ++m) _Pragma("unroll") for (int n = 0; n < 2; ++n) _Pragma("unroll") for (int k = 0; k < 2; ++k) \
;         acc[ai][bj][m][n] = __builtin_amdgcn_mfma_f32_16x16x32_bf16(Bt[n][k], At[m][k], acc[ai][bj][m][n], 0, 0, 0); __builtin_amdgcn_s_setprio(0); } while (0)
; #define PG8_WAIT_V(n) asm volatile("s_waitcnt vmcnt(" #n ")" ::: "memory")
; #define PG8_WAIT_L(n) asm volatile("s_waitcnt lgkmcnt(" #n ")" ::: "memory")
; #define PG8_BAR __builtin_amdgcn_s_barrier()
; #define PG8_SCHED __builtin_amdgcn_sched_barrier(0)
; template <class Epi, class Sched, bool ALIGN_EPI = false, bool SP2 = false, bool RS = false, bool BPRE = false>
; __device__ __forceinline__ void gemm_phase(PG8_LAS unsigned char* lds, const Gemm g, const Sched& S, const Epi& E, const float* rs_ss = nullptr, PG8_LAS float* rs_tab = nullptr) {
;     ...
;             PG8_LDB(B0, 1, 0); PG8_LDB(B1, 1, 1); PG8_SCHED; PG8_LDA(At, 1, 0); PG8_STAGE(PG8_SA(0, 1), a2 + hstep, voffA);
;             PG8_WAIT_V(8); PG8_WAIT_L(0); PG8_BAR; PG8_MMA(0, 0, At, B0); PG8_MMA(0, 1, At, B1); PG8_BAR; PG8_SCHED;
	s_add_i32 s74, 0, 0x18000
	v_add_u32_e32 v3, s74, v150
	s_add_i32 s75, 0, 0x1c000
	ds_read_b128 v[160:163], v3
	ds_read_b128 v[164:167], v3 offset:1024
	ds_read_b128 v[168:171], v3 offset:2048
	ds_read_b128 v[172:175], v3 offset:3072
	v_add_u32_e32 v3, s75, v150
	ds_read_b128 v[176:179], v3
	ds_read_b128 v[180:183], v3 offset:1024
	ds_read_b128 v[184:187], v3 offset:2048
	ds_read_b128 v[188:191], v3 offset:3072
	s_add_u32 s42, s42, 0xc0000
	s_addc_u32 s43, s43, 0
	s_mov_b32 m0, s57
	v_lshl_add_u64 v[8:9], s[42:43], 0, v[134:135]
	ds_read_b128 v[192:195], v154 offset:32768
	ds_read_b128 v[196:199], v154 offset:33792
	ds_read_b128 v[200:203], v154 offset:34816
	ds_read_b128 v[204:207], v154 offset:35840
	ds_read_b128 v[208:211], v154 offset:36864
	ds_read_b128 v[212:215], v154 offset:37888
	ds_read_b128 v[216:219], v154 offset:38912
	ds_read_b128 v[220:223], v154 offset:39936
	global_load_lds_dwordx4 v[8:9], off
	v_lshl_add_u64 v[8:9], s[42:43], 0, v[136:137]
	s_mov_b32 m0, s58
	s_nop 0
	global_load_lds_dwordx4 v[8:9], off
	s_waitcnt vmcnt(8)
	s_waitcnt lgkmcnt(0)
	s_barrier
	s_setprio 1
	s_waitcnt lgkmcnt(0)
	v_mfma_f32_16x16x32_bf16 v[130:133], v[160:163], v[192:195], v[130:133]
	v_mfma_f32_16x16x32_bf16 v[130:133], v[164:167], v[196:199], v[130:133]
	v_mfma_f32_16x16x32_bf16 v[126:129], v[172:175], v[196:199], v[126:129]
	v_mfma_f32_16x16x32_bf16 v[126:129], v[168:171], v[192:195], v[126:129]
	v_mfma_f32_16x16x32_bf16 v[110:113], v[168:171], v[200:203], v[110:113]
	v_mfma_f32_16x16x32_bf16 v[110:113], v[172:175], v[204:207], v[110:113]
	v_mfma_f32_16x16x32_bf16 v[114:117], v[164:167], v[204:207], v[114:117]
	v_mfma_f32_16x16x32_bf16 v[114:117], v[160:163], v[200:203], v[114:117]
	v_mfma_f32_16x16x32_bf16 v[98:101], v[160:163], v[208:211], v[98:101]
	v_mfma_f32_16x16x32_bf16 v[98:101], v[164:167], v[212:215], v[98:101]
	v_mfma_f32_16x16x32_bf16 v[94:97], v[172:175], v[212:215], v[94:97]
	v_mfma_f32_16x16x32_bf16 v[94:97], v[168:171], v[208:211], v[94:97]
	v_mfma_f32_16x16x32_bf16 v[78:81], v[168:171], v[216:219], v[78:81]
	v_mfma_f32_16x16x32_bf16 v[78:81], v[172:175], v[220:223], v[78:81]
	v_mfma_f32_16x16x32_bf16 v[82:85], v[164:167], v[220:223], v[82:85]
	v_mfma_f32_16x16x32_bf16 v[82:85], v[160:163], v[216:219], v[82:85]
	v_mfma_f32_16x16x32_bf16 v[74:77], v[176:179], v[216:219], v[74:77]
	v_mfma_f32_16x16x32_bf16 v[74:77], v[180:183], v[220:223], v[74:77]
	v_mfma_f32_16x16x32_bf16 v[70:73], v[188:191], v[220:223], v[70:73]
	v_mfma_f32_16x16x32_bf16 v[70:73], v[184:187], v[216:219], v[70:73]
	v_mfma_f32_16x16x32_bf16 v[86:89], v[184:187], v[208:211], v[86:89]
	v_mfma_f32_16x16x32_bf16 v[86:89], v[188:191], v[212:215], v[86:89]
	v_mfma_f32_16x16x32_bf16 v[90:93], v[180:183], v[212:215], v[90:93]
	v_mfma_f32_16x16x32_bf16 v[90:93], v[176:179], v[208:211], v[90:93]
	v_mfma_f32_16x16x32_bf16 v[106:109], v[176:179], v[200:203], v[106:109]
	v_mfma_f32_16x16x32_bf16 v[106:109], v[180:183], v[204:207], v[106:109]
	v_mfma_f32_16x16x32_bf16 v[102:105], v[188:191], v[204:207], v[102:105]
	v_mfma_f32_16x16x32_bf16 v[102:105], v[184:187], v[200:203], v[102:105]
	v_mfma_f32_16x16x32_bf16 v[118:121], v[184:187], v[192:195], v[118:121]
	v_mfma_f32_16x16x32_bf16 v[118:121], v[188:191], v[196:199], v[118:121]
	v_mfma_f32_16x16x32_bf16 v[122:125], v[180:183], v[196:199], v[122:125]
	v_mfma_f32_16x16x32_bf16 v[122:125], v[176:179], v[192:195], v[122:125]
	s_setprio 0
	s_barrier
; #define PG8_STAGE(bufoff, gbase, voff) do { _Pragma("unroll") for (int _i = 0; _i < 2; ++_i) \
;         __builtin_amdgcn_global_load_lds((const unsigned*)((const char*)(gbase) + (voff)[_i]), (PG8_LAS unsigned*)(lds + (bufoff) + ldsw + _i * 8192), 16, 0, 0); } while (0)
; #define PG8_LDA(dst, b, h) do { _Pragma("unroll") for (int m = 0; m < 4; ++m) _Pragma("unroll") for (int k = 0; k < 2; ++k) dst[m][k] = *(const PG8_LAS bf16x8*)(lds + PG8_SA(b, h) + aoff + m * 2048 + k * 1024); } while (0)
; #define PG8_MMA(ai, bj, At, Bt) do { __builtin_amdgcn_s_setprio(1); _Pragma("unroll") for (int m = 0; m < 4; ++m) _Pragma("unroll") for (int n = 0; n < 2; ++n) _Pragma("unroll") for (int k = 0; k < 2; ++k) \
;         acc[ai][bj][m][n] = __builtin_amdgcn_mfma_f32_16x16x32_bf16(Bt[n][k], At[m][k], acc[ai][bj][m][n], 0, 0, 0); __builtin_amdgcn_s_setprio(0); } while (0)
; #define PG8_WAIT_V(n) asm volatile("s_waitcnt vmcnt(" #n ")" ::: "memory")
; #define PG8_WAIT_L(n) asm volatile("s_waitcnt lgkmcnt(" #n ")" ::: "memory")
; #define PG8_BAR __builtin_amdgcn_s_barrier()
; #define PG8_SCHED __builtin_amdgcn_sched_barrier(0)
; template <class Epi, class Sched, bool ALIGN_EPI = false, bool SP2 = false, bool RS = false, bool BPRE = false>
; __device__ __forceinline__ void gemm_phase(PG8_LAS unsigned char* lds, const Gemm g, const Sched& S, const Epi& E, const float* rs_ss = nullptr, PG8_LAS float* rs_tab = nullptr) {
;     ...
;         for (int t = 0; t < nt; t += 2) {
;     ...
;             PG8_LDA(At, 1, 1); PG8_STAGE(PG8_SB(1, 0), b3, voffB); PG8_STAGE(PG8_SB(1, 1), b3 + hstep, voffB); PG8_STAGE(PG8_SA(1, 0), a3, voffA);
;             PG8_WAIT_V(8); PG8_WAIT_L(0); PG8_BAR; PG8_MMA(1, 0, At, B0); PG8_MMA(1, 1, At, B1); PG8_BAR; PG8_SCHED;
	s_add_u32 s42, s40, 0x4000
	s_addc_u32 s43, s41, 0
	s_add_i32 s74, s74, s54
	v_lshl_add_u64 v[8:9], s[42:43], 0, v[134:135]
	s_mov_b32 m0, s74
	ds_read_b128 v[192:195], v154 offset:49152
	ds_read_b128 v[196:199], v154 offset:50176
	ds_read_b128 v[200:203], v154 offset:51200
	ds_read_b128 v[204:207], v154 offset:52224
	ds_read_b128 v[208:211], v154 offset:53248
	ds_read_b128 v[212:215], v154 offset:54272
	ds_read_b128 v[216:219], v154 offset:55296
	ds_read_b128 v[220:223], v154 offset:56320
	global_load_lds_dwordx4 v[8:9], off
	s_add_i32 m0, s74, 0x2000
	s_add_u32 s40, s40, 0xc4000
	v_lshl_add_u64 v[8:9], s[42:43], 0, v[136:137]
	s_addc_u32 s41, s41, 0
	s_add_i32 s42, s75, s54
	global_load_lds_dwordx4 v[8:9], off
	v_lshl_add_u64 v[8:9], s[40:41], 0, v[134:135]
	s_mov_b32 m0, s42
	s_nop 0
	global_load_lds_dwordx4 v[8:9], off
	v_lshl_add_u64 v[8:9], s[40:41], 0, v[136:137]
	s_add_i32 m0, s42, 0x2000
	s_nop 0
	global_load_lds_dwordx4 v[8:9], off
	v_lshl_add_u64 v[8:9], s[38:39], 0, v[134:135]
	s_mov_b32 m0, s60
	s_nop 0
	global_load_lds_dwordx4 v[8:9], off
	v_lshl_add_u64 v[8:9], s[38:39], 0, v[136:137]
	s_mov_b32 m0, s61
	s_nop 0
	global_load_lds_dwordx4 v[8:9], off
	s_waitcnt vmcnt(8)
	s_waitcnt lgkmcnt(0)
	s_barrier
	s_setprio 1
	s_waitcnt lgkmcnt(0)
	v_mfma_f32_16x16x32_bf16 v[66:69], v[160:163], v[192:195], v[66:69]
	v_mfma_f32_16x16x32_bf16 v[66:69], v[164:167], v[196:199], v[66:69]
	v_mfma_f32_16x16x32_bf16 v[62:65], v[172:175], v[196:199], v[62:65]
	v_mfma_f32_16x16x32_bf16 v[62:65], v[168:171], v[192:195], v[62:65]
	v_mfma_f32_16x16x32_bf16 v[46:49], v[168:171], v[200:203], v[46:49]
	v_mfma_f32_16x16x32_bf16 v[46:49], v[172:175], v[204:207], v[46:49]
	v_mfma_f32_16x16x32_bf16 v[50:53], v[164:167], v[204:207], v[50:53]
	v_mfma_f32_16x16x32_bf16 v[50:53], v[160:163], v[200:203], v[50:53]
	v_mfma_f32_16x16x32_bf16 v[34:37], v[160:163], v[208:211], v[34:37]
	v_mfma_f32_16x16x32_bf16 v[34:37], v[164:167], v[212:215], v[34:37]
	v_mfma_f32_16x16x32_bf16 v[30:33], v[172:175], v[212:215], v[30:33]
	v_mfma_f32_16x16x32_bf16 v[30:33], v[168:171], v[208:211], v[30:33]
	v_mfma_f32_16x16x32_bf16 v[14:17], v[168:171], v[216:219], v[14:17]
	v_mfma_f32_16x16x32_bf16 v[14:17], v[172:175], v[220:223], v[14:17]
	v_mfma_f32_16x16x32_bf16 v[18:21], v[164:167], v[220:223], v[18:21]
	v_mfma_f32_16x16x32_bf16 v[18:21], v[160:163], v[216:219], v[18:21]
	v_mfma_f32_16x16x32_bf16 v[58:61], v[176:179], v[192:195], v[58:61]
	v_mfma_f32_16x16x32_bf16 v[58:61], v[180:183], v[196:199], v[58:61]
	v_mfma_f32_16x16x32_bf16 v[54:57], v[188:191], v[196:199], v[54:57]
	v_mfma_f32_16x16x32_bf16 v[54:57], v[184:187], v[192:195], v[54:57]
	v_mfma_f32_16x16x32_bf16 v[38:41], v[184:187], v[200:203], v[38:41]
	v_mfma_f32_16x16x32_bf16 v[38:41], v[188:191], v[204:207], v[38:41]
	v_mfma_f32_16x16x32_bf16 v[42:45], v[180:183], v[204:207], v[42:45]
	v_mfma_f32_16x16x32_bf16 v[42:45], v[176:179], v[200:203], v[42:45]
	v_mfma_f32_16x16x32_bf16 v[26:29], v[176:179], v[208:211], v[26:29]
	v_mfma_f32_16x16x32_bf16 v[26:29], v[180:183], v[212:215], v[26:29]
	v_mfma_f32_16x16x32_bf16 v[22:25], v[188:191], v[212:215], v[22:25]
	v_mfma_f32_16x16x32_bf16 v[22:25], v[184:187], v[208:211], v[22:25]
	v_mfma_f32_16x16x32_bf16 v[8:11], v[176:179], v[216:219], v[10:13]
	v_mfma_f32_16x16x32_bf16 v[10:13], v[180:183], v[220:223], v[8:11]
	v_mfma_f32_16x16x32_bf16 v[4:7], v[188:191], v[220:223], v[4:7]
	v_mfma_f32_16x16x32_bf16 v[6:9], v[184:187], v[216:219], v[4:7]
	s_setprio 0
	s_barrier
	s_add_i32 s38, s73, 2
	s_add_u32 s6, s6, 0x8000
	s_addc_u32 s7, s7, 0
	s_cmp_gt_u32 s73, 45
	s_mov_b32 s73, s38
	s_cbranch_scc1 .LBB0_759
